# grid barrier: acquire-side invalidate issued at barrier entry (overlaps the wait); K-loop DMA loads use scalar base + lane offset
# speedup vs baseline: 1.0367x; 1.0148x over previous
.LBB0_65:
	s_cbranch_execz .LBB0_119
	s_waitcnt vmcnt(0)
	v_readfirstlane_b32 s3, v170
	s_nop 0
	s_cmp_gt_u32 s3, 63
	s_cbranch_scc1 .Lei_0
	buffer_inv sc1
.Lei_0:
	s_barrier
	s_mov_b64 s[8:9], exec
	v_readlane_b32 s6, v255, 4
	v_readlane_b32 s7, v255, 5
	s_and_b64 s[6:7], s[8:9], s[6:7]
	s_mov_b64 exec, s[6:7]
	s_cbranch_execz .LBB0_118
	s_add_i32 s3, 0, 0x22020
	v_mov_b32_e32 v1, s3
	s_waitcnt lgkmcnt(0)
	ds_read_b32 v4, v1
	s_add_i32 s3, 0, 0x22024
	v_mov_b32_e32 v1, s3
	ds_read_b32 v2, v1
	s_waitcnt lgkmcnt(1)
	v_cmp_ne_u32_e32 vcc, 0, v4
	s_cbranch_vccnz .LBB0_82
	v_readlane_b32 s10, v255, 1
	v_readlane_b32 s11, v255, 2
	s_load_dwordx2 s[6:7], s[10:11], 0x4
	s_add_u32 s10, s88, 0x1200
	s_addc_u32 s11, s89, 0
	s_add_u32 s12, s88, 0x1400
	s_addc_u32 s13, s89, 0
	s_add_u32 s14, s88, 0x1500
	s_addc_u32 s15, s89, 0
	s_add_u32 s16, s88, 0x1600
	s_addc_u32 s17, s89, 0
	s_add_u32 s18, s88, 0x1700
	s_addc_u32 s19, s89, 0
	s_add_u32 s20, s88, 0x1800
	s_addc_u32 s21, s89, 0
	s_add_u32 s22, s88, 0x1900
	s_addc_u32 s23, s89, 0
	s_add_u32 s24, s88, 0x1a00
	s_addc_u32 s25, s89, 0
	s_add_u32 s26, s88, 0x1b00
	s_addc_u32 s27, s89, 0
	s_add_u32 s28, s88, 0x1c00
	s_addc_u32 s29, s89, 0
	s_add_u32 s30, s88, 0x1d00
	s_addc_u32 s31, s89, 0
	s_add_u32 s34, s88, 0x1e00
	s_addc_u32 s35, s89, 0
	s_add_u32 s36, s88, 0x1f00
	s_addc_u32 s37, s89, 0
	s_add_u32 s38, s88, 0x2000
	s_addc_u32 s39, s89, 0
	s_add_u32 s40, s88, 0x2100
	s_addc_u32 s41, s89, 0
	s_add_u32 s42, s88, 0x2200
	s_addc_u32 s43, s89, 0
	s_waitcnt lgkmcnt(0)
	s_mul_i32 s3, s6, s33
	s_add_u32 s44, s88, 0x2300
	s_mul_i32 s3, s3, s7
	s_addc_u32 s45, s89, 0
	s_mov_b32 s6, 1
	v_mov_b32_e32 v18, 0
	s_branch .LBB0_70

.LBB0_97:
	s_or_b64 exec, exec, s[14:15]
	s_waitcnt vmcnt(0) lgkmcnt(0)
	s_waitcnt vmcnt(0)

.LBB0_115:
	s_or_b64 exec, exec, s[12:13]
	s_mov_b64 s[12:13], exec
	v_mbcnt_lo_u32_b32 v1, s12, 0
	v_mbcnt_hi_u32_b32 v1, s13, v1
	v_cmp_eq_u32_e32 vcc, 0, v1
	s_waitcnt vmcnt(0)
	s_and_saveexec_b64 s[14:15], vcc
	s_cbranch_execz .LBB0_117
	s_bcnt1_i32_b64 s3, s[12:13]
	v_mov_b32_e32 v1, 0x2000
	v_mov_b32_e32 v2, s3
	global_atomic_add v1, v2, s[10:11] offset:1024

.LBB0_147:
	s_cbranch_execz .LBB0_201
	s_waitcnt vmcnt(0)
	s_waitcnt lgkmcnt(0)
	v_readfirstlane_b32 s3, v170
	s_nop 0
	s_cmp_gt_u32 s3, 63
	s_cbranch_scc1 .Lei_1
	buffer_inv sc1
.Lei_1:
	s_barrier
	s_mov_b64 s[4:5], exec
	v_readlane_b32 s6, v255, 4
	v_readlane_b32 s7, v255, 5
	s_and_b64 s[6:7], s[4:5], s[6:7]
	s_mov_b64 exec, s[6:7]
	s_cbranch_execz .LBB0_200
	s_add_i32 s3, 0, 0x22020
	v_mov_b32_e32 v1, s3
	s_waitcnt lgkmcnt(0)
	ds_read_b32 v4, v1
	s_add_i32 s3, 0, 0x22024
	v_mov_b32_e32 v1, s3
	ds_read_b32 v2, v1
	s_waitcnt lgkmcnt(1)
	v_cmp_ne_u32_e32 vcc, 0, v4
	s_cbranch_vccnz .LBB0_164
	v_readlane_b32 s8, v255, 1
	v_readlane_b32 s9, v255, 2
	s_load_dwordx2 s[6:7], s[8:9], 0x4
	s_add_u32 s8, s88, 0x1200
	s_addc_u32 s9, s89, 0
	s_add_u32 s10, s88, 0x1400
	s_addc_u32 s11, s89, 0
	s_add_u32 s12, s88, 0x1500
	s_addc_u32 s13, s89, 0
	s_add_u32 s14, s88, 0x1600
	s_addc_u32 s15, s89, 0
	s_add_u32 s16, s88, 0x1700
	s_addc_u32 s17, s89, 0
	s_add_u32 s18, s88, 0x1800
	s_addc_u32 s19, s89, 0
	s_add_u32 s20, s88, 0x1900
	s_addc_u32 s21, s89, 0
	s_add_u32 s22, s88, 0x1a00
	s_addc_u32 s23, s89, 0
	s_add_u32 s24, s88, 0x1b00
	s_addc_u32 s25, s89, 0
	s_add_u32 s26, s88, 0x1c00
	s_addc_u32 s27, s89, 0
	s_add_u32 s28, s88, 0x1d00
	s_addc_u32 s29, s89, 0
	s_add_u32 s30, s88, 0x1e00
	s_addc_u32 s31, s89, 0
	s_add_u32 s34, s88, 0x1f00
	s_addc_u32 s35, s89, 0
	s_add_u32 s36, s88, 0x2000
	s_addc_u32 s37, s89, 0
	s_add_u32 s38, s88, 0x2100
	s_addc_u32 s39, s89, 0
	s_add_u32 s40, s88, 0x2200
	s_addc_u32 s41, s89, 0
	s_waitcnt lgkmcnt(0)
	s_mul_i32 s3, s6, s33
	s_add_u32 s42, s88, 0x2300
	s_mul_i32 s3, s3, s7
	s_addc_u32 s43, s89, 0
	s_mov_b32 s6, 1
	v_mov_b32_e32 v18, 0
	s_branch .LBB0_152

.LBB0_179:
	s_or_b64 exec, exec, s[12:13]
	s_waitcnt vmcnt(0) lgkmcnt(0)
	s_waitcnt vmcnt(0)

.LBB0_197:
	s_or_b64 exec, exec, s[10:11]
	s_mov_b64 s[10:11], exec
	v_mbcnt_lo_u32_b32 v1, s10, 0
	v_mbcnt_hi_u32_b32 v1, s11, v1
	v_cmp_eq_u32_e32 vcc, 0, v1
	s_waitcnt vmcnt(0)
	s_and_saveexec_b64 s[12:13], vcc
	s_cbranch_execz .LBB0_199
	s_bcnt1_i32_b64 s3, s[10:11]
	v_mov_b32_e32 v1, 0x2000
	v_mov_b32_e32 v2, s3
	global_atomic_add v1, v2, s[8:9] offset:1024

.LBB0_212:
	ds_read_b128 v[146:149], v153
	ds_read_b128 v[156:159], v153 offset:1024
	ds_read_b128 v[160:163], v153 offset:2048
	ds_read_b128 v[164:167], v153 offset:3072
	ds_read_b128 v[174:177], v154
	ds_read_b128 v[178:181], v154 offset:1024
	ds_read_b128 v[182:185], v154 offset:2048
	ds_read_b128 v[186:189], v154 offset:3072
	s_add_u32 s26, s24, 0xfffc0080
	s_addc_u32 s27, s25, -1
	s_cmp_eq_u32 s70, 12
	s_cselect_b32 s29, s17, s27
	s_cselect_b32 s28, s44, s26
	s_cselect_b32 s27, s15, s47
	s_cselect_b32 s26, s45, s46
	s_add_i32 m0, s23, 0xc000
	ds_read_b128 v[190:193], v155
	ds_read_b128 v[194:197], v155 offset:1024
	ds_read_b128 v[198:201], v155 offset:2048
	ds_read_b128 v[202:205], v155 offset:3072
	ds_read_b128 v[206:209], v155 offset:4096
	ds_read_b128 v[210:213], v155 offset:5120
	ds_read_b128 v[214:217], v155 offset:6144
	ds_read_b128 v[218:221], v155 offset:7168
	global_load_lds_dwordx4 v138, s[24:25]
	s_add_i32 m0, s23, 0xe000
	s_nop 0
	global_load_lds_dwordx4 v140, s[24:25]
	s_waitcnt vmcnt(8)
	s_waitcnt lgkmcnt(0)
	s_barrier
	s_setprio 1
	v_mfma_f32_16x16x32_bf16 v[126:129], v[146:149], v[190:193], v[126:129]
	v_mfma_f32_16x16x32_bf16 v[122:125], v[160:163], v[190:193], v[122:125]
	v_mfma_f32_16x16x32_bf16 v[118:121], v[146:149], v[198:201], v[118:121]
	v_mfma_f32_16x16x32_bf16 v[110:113], v[160:163], v[198:201], v[110:113]
	v_mfma_f32_16x16x32_bf16 v[102:105], v[146:149], v[206:209], v[102:105]
	v_mfma_f32_16x16x32_bf16 v[94:97], v[160:163], v[206:209], v[94:97]
	v_mfma_f32_16x16x32_bf16 v[86:89], v[146:149], v[214:217], v[86:89]
	v_mfma_f32_16x16x32_bf16 v[78:81], v[160:163], v[214:217], v[78:81]
	v_mfma_f32_16x16x32_bf16 v[126:129], v[156:159], v[194:197], v[126:129]
	v_mfma_f32_16x16x32_bf16 v[122:125], v[164:167], v[194:197], v[122:125]
	v_mfma_f32_16x16x32_bf16 v[118:121], v[156:159], v[202:205], v[118:121]
	v_mfma_f32_16x16x32_bf16 v[110:113], v[164:167], v[202:205], v[110:113]
	v_mfma_f32_16x16x32_bf16 v[102:105], v[156:159], v[210:213], v[102:105]
	v_mfma_f32_16x16x32_bf16 v[94:97], v[164:167], v[210:213], v[94:97]
	v_mfma_f32_16x16x32_bf16 v[86:89], v[156:159], v[218:221], v[86:89]
	v_mfma_f32_16x16x32_bf16 v[78:81], v[164:167], v[218:221], v[78:81]
	v_mfma_f32_16x16x32_bf16 v[114:117], v[174:177], v[190:193], v[114:117]
	v_mfma_f32_16x16x32_bf16 v[106:109], v[182:185], v[190:193], v[106:109]
	v_mfma_f32_16x16x32_bf16 v[98:101], v[174:177], v[198:201], v[98:101]
	v_mfma_f32_16x16x32_bf16 v[90:93], v[182:185], v[198:201], v[90:93]
	v_mfma_f32_16x16x32_bf16 v[82:85], v[174:177], v[206:209], v[82:85]
	v_mfma_f32_16x16x32_bf16 v[74:77], v[182:185], v[206:209], v[74:77]
	v_mfma_f32_16x16x32_bf16 v[70:73], v[174:177], v[214:217], v[70:73]
	v_mfma_f32_16x16x32_bf16 v[66:69], v[182:185], v[214:217], v[66:69]
	v_mfma_f32_16x16x32_bf16 v[114:117], v[178:181], v[194:197], v[114:117]
	v_mfma_f32_16x16x32_bf16 v[106:109], v[186:189], v[194:197], v[106:109]
	v_mfma_f32_16x16x32_bf16 v[98:101], v[178:181], v[202:205], v[98:101]
	v_mfma_f32_16x16x32_bf16 v[90:93], v[186:189], v[202:205], v[90:93]
	v_mfma_f32_16x16x32_bf16 v[82:85], v[178:181], v[210:213], v[82:85]
	v_mfma_f32_16x16x32_bf16 v[74:77], v[186:189], v[210:213], v[74:77]
	v_mfma_f32_16x16x32_bf16 v[70:73], v[178:181], v[218:221], v[70:73]
	v_mfma_f32_16x16x32_bf16 v[66:69], v[186:189], v[218:221], v[66:69]
	s_setprio 0
	s_barrier
	s_add_u32 s98, s26, 0x80
	s_addc_u32 s99, s27, 0
	s_add_u32 s100, s28, 0x80
	s_addc_u32 s101, s29, 0
	s_add_i32 s71, s40, s7
	s_mov_b32 m0, s71
	ds_read_b128 v[190:193], v155 offset:16384
	ds_read_b128 v[194:197], v155 offset:17408
	ds_read_b128 v[198:201], v155 offset:18432
	ds_read_b128 v[202:205], v155 offset:19456
	ds_read_b128 v[206:209], v155 offset:20480
	ds_read_b128 v[210:213], v155 offset:21504
	ds_read_b128 v[214:217], v155 offset:22528
	ds_read_b128 v[218:221], v155 offset:23552
	global_load_lds_dwordx4 v134, s[26:27]
	s_add_i32 m0, s71, 0x2000
	s_add_u32 s74, s26, 0x40000
	s_addc_u32 s75, s27, 0
	s_add_i32 s71, s41, s7
	global_load_lds_dwordx4 v130, s[26:27]
	s_mov_b32 m0, s71
	s_nop 0
	global_load_lds_dwordx4 v134, s[74:75]
	s_add_i32 m0, s71, 0x2000
	s_nop 0
	global_load_lds_dwordx4 v130, s[74:75]
	s_mov_b32 m0, s23
	s_nop 0
	global_load_lds_dwordx4 v136, s[28:29]
	s_mov_b32 m0, s31
	s_nop 0
	global_load_lds_dwordx4 v132, s[28:29]
	s_waitcnt vmcnt(8)
	s_waitcnt lgkmcnt(0)
	s_barrier
	s_setprio 1
	v_mfma_f32_16x16x32_bf16 v[62:65], v[146:149], v[190:193], v[62:65]
	v_mfma_f32_16x16x32_bf16 v[58:61], v[160:163], v[190:193], v[58:61]
	v_mfma_f32_16x16x32_bf16 v[54:57], v[146:149], v[198:201], v[54:57]
	v_mfma_f32_16x16x32_bf16 v[46:49], v[160:163], v[198:201], v[46:49]
	v_mfma_f32_16x16x32_bf16 v[38:41], v[146:149], v[206:209], v[38:41]
	v_mfma_f32_16x16x32_bf16 v[30:33], v[160:163], v[206:209], v[30:33]
	v_mfma_f32_16x16x32_bf16 v[22:25], v[146:149], v[214:217], v[22:25]
	v_mfma_f32_16x16x32_bf16 v[14:17], v[160:163], v[214:217], v[14:17]
	v_mfma_f32_16x16x32_bf16 v[62:65], v[156:159], v[194:197], v[62:65]
	v_mfma_f32_16x16x32_bf16 v[58:61], v[164:167], v[194:197], v[58:61]
	v_mfma_f32_16x16x32_bf16 v[54:57], v[156:159], v[202:205], v[54:57]
	v_mfma_f32_16x16x32_bf16 v[46:49], v[164:167], v[202:205], v[46:49]
	v_mfma_f32_16x16x32_bf16 v[38:41], v[156:159], v[210:213], v[38:41]
	v_mfma_f32_16x16x32_bf16 v[30:33], v[164:167], v[210:213], v[30:33]
	v_mfma_f32_16x16x32_bf16 v[22:25], v[156:159], v[218:221], v[22:25]
	v_mfma_f32_16x16x32_bf16 v[14:17], v[164:167], v[218:221], v[14:17]
	v_mfma_f32_16x16x32_bf16 v[50:53], v[174:177], v[190:193], v[50:53]
	v_mfma_f32_16x16x32_bf16 v[42:45], v[182:185], v[190:193], v[42:45]
	v_mfma_f32_16x16x32_bf16 v[34:37], v[174:177], v[198:201], v[34:37]
	v_mfma_f32_16x16x32_bf16 v[26:29], v[182:185], v[198:201], v[26:29]
	v_mfma_f32_16x16x32_bf16 v[18:21], v[174:177], v[206:209], v[18:21]
	v_mfma_f32_16x16x32_bf16 v[10:13], v[182:185], v[206:209], v[10:13]
	v_mfma_f32_16x16x32_bf16 v[6:9], v[174:177], v[214:217], v[6:9]
	v_mfma_f32_16x16x32_bf16 v[2:5], v[182:185], v[214:217], v[2:5]
	v_mfma_f32_16x16x32_bf16 v[50:53], v[178:181], v[194:197], v[50:53]
	v_mfma_f32_16x16x32_bf16 v[42:45], v[186:189], v[194:197], v[42:45]
	v_mfma_f32_16x16x32_bf16 v[34:37], v[178:181], v[202:205], v[34:37]
	v_mfma_f32_16x16x32_bf16 v[26:29], v[186:189], v[202:205], v[26:29]
	v_mfma_f32_16x16x32_bf16 v[18:21], v[178:181], v[210:213], v[18:21]
	v_mfma_f32_16x16x32_bf16 v[10:13], v[186:189], v[210:213], v[10:13]
	v_mfma_f32_16x16x32_bf16 v[6:9], v[178:181], v[218:221], v[6:9]
	v_mfma_f32_16x16x32_bf16 v[2:5], v[186:189], v[218:221], v[2:5]
	s_setprio 0
	s_barrier
	s_add_i32 s71, 0, 0x18000
	v_add_u32_e32 v1, s71, v151
	s_add_i32 s74, 0, 0x1c000
	ds_read_b128 v[146:149], v1
	ds_read_b128 v[156:159], v1 offset:1024
	ds_read_b128 v[160:163], v1 offset:2048
	ds_read_b128 v[164:167], v1 offset:3072
	v_add_u32_e32 v1, s74, v151
	ds_read_b128 v[174:177], v1
	ds_read_b128 v[178:181], v1 offset:1024
	ds_read_b128 v[182:185], v1 offset:2048
	ds_read_b128 v[186:189], v1 offset:3072
	s_add_u32 s28, s28, 0x40000
	s_addc_u32 s29, s29, 0
	s_mov_b32 m0, s34
	ds_read_b128 v[190:193], v155 offset:32768
	ds_read_b128 v[194:197], v155 offset:33792
	ds_read_b128 v[198:201], v155 offset:34816
	ds_read_b128 v[202:205], v155 offset:35840
	ds_read_b128 v[206:209], v155 offset:36864
	ds_read_b128 v[210:213], v155 offset:37888
	ds_read_b128 v[214:217], v155 offset:38912
	ds_read_b128 v[218:221], v155 offset:39936
	global_load_lds_dwordx4 v136, s[28:29]
	s_mov_b32 m0, s35
	s_nop 0
	global_load_lds_dwordx4 v132, s[28:29]
	s_waitcnt vmcnt(8)
	s_waitcnt lgkmcnt(0)
	s_barrier
	s_setprio 1
	v_mfma_f32_16x16x32_bf16 v[126:129], v[146:149], v[190:193], v[126:129]
	v_mfma_f32_16x16x32_bf16 v[122:125], v[160:163], v[190:193], v[122:125]
	v_mfma_f32_16x16x32_bf16 v[118:121], v[146:149], v[198:201], v[118:121]
	v_mfma_f32_16x16x32_bf16 v[110:113], v[160:163], v[198:201], v[110:113]
	v_mfma_f32_16x16x32_bf16 v[102:105], v[146:149], v[206:209], v[102:105]
	v_mfma_f32_16x16x32_bf16 v[94:97], v[160:163], v[206:209], v[94:97]
	v_mfma_f32_16x16x32_bf16 v[86:89], v[146:149], v[214:217], v[86:89]
	v_mfma_f32_16x16x32_bf16 v[78:81], v[160:163], v[214:217], v[78:81]
	v_mfma_f32_16x16x32_bf16 v[126:129], v[156:159], v[194:197], v[126:129]
	v_mfma_f32_16x16x32_bf16 v[122:125], v[164:167], v[194:197], v[122:125]
	v_mfma_f32_16x16x32_bf16 v[118:121], v[156:159], v[202:205], v[118:121]
	v_mfma_f32_16x16x32_bf16 v[110:113], v[164:167], v[202:205], v[110:113]
	v_mfma_f32_16x16x32_bf16 v[102:105], v[156:159], v[210:213], v[102:105]
	v_mfma_f32_16x16x32_bf16 v[94:97], v[164:167], v[210:213], v[94:97]
	v_mfma_f32_16x16x32_bf16 v[86:89], v[156:159], v[218:221], v[86:89]
	v_mfma_f32_16x16x32_bf16 v[78:81], v[164:167], v[218:221], v[78:81]
	v_mfma_f32_16x16x32_bf16 v[114:117], v[174:177], v[190:193], v[114:117]
	v_mfma_f32_16x16x32_bf16 v[106:109], v[182:185], v[190:193], v[106:109]
	v_mfma_f32_16x16x32_bf16 v[98:101], v[174:177], v[198:201], v[98:101]
	v_mfma_f32_16x16x32_bf16 v[90:93], v[182:185], v[198:201], v[90:93]
	v_mfma_f32_16x16x32_bf16 v[82:85], v[174:177], v[206:209], v[82:85]
	v_mfma_f32_16x16x32_bf16 v[74:77], v[182:185], v[206:209], v[74:77]
	v_mfma_f32_16x16x32_bf16 v[70:73], v[174:177], v[214:217], v[70:73]
	v_mfma_f32_16x16x32_bf16 v[66:69], v[182:185], v[214:217], v[66:69]
	v_mfma_f32_16x16x32_bf16 v[114:117], v[178:181], v[194:197], v[114:117]
	v_mfma_f32_16x16x32_bf16 v[106:109], v[186:189], v[194:197], v[106:109]
	v_mfma_f32_16x16x32_bf16 v[98:101], v[178:181], v[202:205], v[98:101]
	v_mfma_f32_16x16x32_bf16 v[90:93], v[186:189], v[202:205], v[90:93]
	v_mfma_f32_16x16x32_bf16 v[82:85], v[178:181], v[210:213], v[82:85]
	v_mfma_f32_16x16x32_bf16 v[74:77], v[186:189], v[210:213], v[74:77]
	v_mfma_f32_16x16x32_bf16 v[70:73], v[178:181], v[218:221], v[70:73]
	v_mfma_f32_16x16x32_bf16 v[66:69], v[186:189], v[218:221], v[66:69]
	s_setprio 0
	s_barrier
	s_add_i32 s28, s71, s7
	s_mov_b32 m0, s28
	ds_read_b128 v[190:193], v155 offset:49152
	ds_read_b128 v[194:197], v155 offset:50176
	ds_read_b128 v[198:201], v155 offset:51200
	ds_read_b128 v[202:205], v155 offset:52224
	ds_read_b128 v[206:209], v155 offset:53248
	ds_read_b128 v[210:213], v155 offset:54272
	ds_read_b128 v[214:217], v155 offset:55296
	ds_read_b128 v[218:221], v155 offset:56320
	global_load_lds_dwordx4 v134, s[98:99]
	s_add_i32 m0, s28, 0x2000
	s_add_u32 s26, s26, 0x40080
	s_addc_u32 s27, s27, 0
	s_add_i32 s28, s74, s7
	global_load_lds_dwordx4 v130, s[98:99]
	s_mov_b32 m0, s28
	s_nop 0
	global_load_lds_dwordx4 v134, s[26:27]
	s_add_i32 m0, s28, 0x2000
	s_nop 0
	global_load_lds_dwordx4 v130, s[26:27]
	s_mov_b32 m0, s37
	s_nop 0
	global_load_lds_dwordx4 v136, s[100:101]
	s_mov_b32 m0, s38
	s_nop 0
	global_load_lds_dwordx4 v132, s[100:101]
	s_waitcnt vmcnt(8)
	s_waitcnt lgkmcnt(0)
	s_barrier
	s_setprio 1
	v_mfma_f32_16x16x32_bf16 v[62:65], v[146:149], v[190:193], v[62:65]
	v_mfma_f32_16x16x32_bf16 v[58:61], v[160:163], v[190:193], v[58:61]
	v_mfma_f32_16x16x32_bf16 v[54:57], v[146:149], v[198:201], v[54:57]
	v_mfma_f32_16x16x32_bf16 v[46:49], v[160:163], v[198:201], v[46:49]
	v_mfma_f32_16x16x32_bf16 v[38:41], v[146:149], v[206:209], v[38:41]
	v_mfma_f32_16x16x32_bf16 v[30:33], v[160:163], v[206:209], v[30:33]
	v_mfma_f32_16x16x32_bf16 v[22:25], v[146:149], v[214:217], v[22:25]
	v_mfma_f32_16x16x32_bf16 v[14:17], v[160:163], v[214:217], v[14:17]
	v_mfma_f32_16x16x32_bf16 v[62:65], v[156:159], v[194:197], v[62:65]
	v_mfma_f32_16x16x32_bf16 v[58:61], v[164:167], v[194:197], v[58:61]
	v_mfma_f32_16x16x32_bf16 v[54:57], v[156:159], v[202:205], v[54:57]
	v_mfma_f32_16x16x32_bf16 v[46:49], v[164:167], v[202:205], v[46:49]
	v_mfma_f32_16x16x32_bf16 v[38:41], v[156:159], v[210:213], v[38:41]
	v_mfma_f32_16x16x32_bf16 v[30:33], v[164:167], v[210:213], v[30:33]
	v_mfma_f32_16x16x32_bf16 v[22:25], v[156:159], v[218:221], v[22:25]
	v_mfma_f32_16x16x32_bf16 v[14:17], v[164:167], v[218:221], v[14:17]
	v_mfma_f32_16x16x32_bf16 v[50:53], v[174:177], v[190:193], v[50:53]
	v_mfma_f32_16x16x32_bf16 v[42:45], v[182:185], v[190:193], v[42:45]
	v_mfma_f32_16x16x32_bf16 v[34:37], v[174:177], v[198:201], v[34:37]
	v_mfma_f32_16x16x32_bf16 v[26:29], v[182:185], v[198:201], v[26:29]
	v_mfma_f32_16x16x32_bf16 v[18:21], v[174:177], v[206:209], v[18:21]
	v_mfma_f32_16x16x32_bf16 v[10:13], v[182:185], v[206:209], v[10:13]
	v_mfma_f32_16x16x32_bf16 v[6:9], v[174:177], v[214:217], v[6:9]
	v_mfma_f32_16x16x32_bf16 v[2:5], v[182:185], v[214:217], v[2:5]
	v_mfma_f32_16x16x32_bf16 v[50:53], v[178:181], v[194:197], v[50:53]
	v_mfma_f32_16x16x32_bf16 v[42:45], v[186:189], v[194:197], v[42:45]
	v_mfma_f32_16x16x32_bf16 v[34:37], v[178:181], v[202:205], v[34:37]
	v_mfma_f32_16x16x32_bf16 v[26:29], v[186:189], v[202:205], v[26:29]
	v_mfma_f32_16x16x32_bf16 v[18:21], v[178:181], v[210:213], v[18:21]
	v_mfma_f32_16x16x32_bf16 v[10:13], v[186:189], v[210:213], v[10:13]
	v_mfma_f32_16x16x32_bf16 v[6:9], v[178:181], v[218:221], v[6:9]
	v_mfma_f32_16x16x32_bf16 v[2:5], v[186:189], v[218:221], v[2:5]
	s_setprio 0
	s_barrier
	s_add_i32 s70, s70, 2
	s_add_u32 s24, s24, 0x100
	s_addc_u32 s25, s25, 0
	s_add_u32 s46, s46, 0x100
	s_addc_u32 s47, s47, 0
	s_cmp_gt_u32 s70, 13
	s_cbranch_scc0 .LBB0_212
	s_and_b64 vcc, exec, s[12:13]
	s_cbranch_vccz .LBB0_215
	s_barrier

.LBB0_450:
	ds_read_b128 v[98:101], v213
	ds_read_b128 v[102:105], v213 offset:1024
	ds_read_b128 v[106:109], v213 offset:2048
	ds_read_b128 v[110:113], v213 offset:3072
	ds_read_b128 v[146:149], v214
	ds_read_b128 v[150:153], v214 offset:1024
	ds_read_b128 v[154:157], v214 offset:2048
	ds_read_b128 v[158:161], v214 offset:3072
	s_add_u32 s34, s30, 0xfffc0080
	s_addc_u32 s35, s31, -1
	s_cmp_eq_u32 s71, 12
	s_cselect_b32 s37, s21, s35
	s_cselect_b32 s36, s27, s34
	s_cselect_b32 s35, s19, s70
	s_cselect_b32 s34, s29, s55
	s_add_i32 m0, s38, 0xc000
	ds_read_b128 v[182:185], v215
	ds_read_b128 v[186:189], v215 offset:1024
	ds_read_b128 v[190:193], v215 offset:2048
	ds_read_b128 v[194:197], v215 offset:3072
	ds_read_b128 v[198:201], v215 offset:4096
	ds_read_b128 v[202:205], v215 offset:5120
	ds_read_b128 v[206:209], v215 offset:6144
	ds_read_b128 v[218:221], v215 offset:7168
	global_load_lds_dwordx4 v174, s[30:31]
	s_add_i32 m0, s38, 0xe000
	s_nop 0
	global_load_lds_dwordx4 v176, s[30:31]
	s_waitcnt vmcnt(8)
	s_waitcnt lgkmcnt(0)
	s_barrier
	s_setprio 1
	v_mfma_f32_16x16x32_bf16 v[142:145], v[98:101], v[182:185], v[142:145]
	v_mfma_f32_16x16x32_bf16 v[138:141], v[106:109], v[182:185], v[138:141]
	v_mfma_f32_16x16x32_bf16 v[126:129], v[98:101], v[190:193], v[126:129]
	v_mfma_f32_16x16x32_bf16 v[122:125], v[106:109], v[190:193], v[122:125]
	v_mfma_f32_16x16x32_bf16 v[94:97], v[98:101], v[198:201], v[94:97]
	v_mfma_f32_16x16x32_bf16 v[90:93], v[106:109], v[198:201], v[90:93]
	v_mfma_f32_16x16x32_bf16 v[78:81], v[98:101], v[206:209], v[78:81]
	v_mfma_f32_16x16x32_bf16 v[74:77], v[106:109], v[206:209], v[74:77]
	v_mfma_f32_16x16x32_bf16 v[142:145], v[102:105], v[186:189], v[142:145]
	v_mfma_f32_16x16x32_bf16 v[138:141], v[110:113], v[186:189], v[138:141]
	v_mfma_f32_16x16x32_bf16 v[126:129], v[102:105], v[194:197], v[126:129]
	v_mfma_f32_16x16x32_bf16 v[122:125], v[110:113], v[194:197], v[122:125]
	v_mfma_f32_16x16x32_bf16 v[94:97], v[102:105], v[202:205], v[94:97]
	v_mfma_f32_16x16x32_bf16 v[90:93], v[110:113], v[202:205], v[90:93]
	v_mfma_f32_16x16x32_bf16 v[78:81], v[102:105], v[218:221], v[78:81]
	v_mfma_f32_16x16x32_bf16 v[74:77], v[110:113], v[218:221], v[74:77]
	v_mfma_f32_16x16x32_bf16 v[134:137], v[146:149], v[182:185], v[134:137]
	v_mfma_f32_16x16x32_bf16 v[130:133], v[154:157], v[182:185], v[130:133]
	v_mfma_f32_16x16x32_bf16 v[118:121], v[146:149], v[190:193], v[118:121]
	v_mfma_f32_16x16x32_bf16 v[114:117], v[154:157], v[190:193], v[114:117]
	v_mfma_f32_16x16x32_bf16 v[86:89], v[146:149], v[198:201], v[86:89]
	v_mfma_f32_16x16x32_bf16 v[82:85], v[154:157], v[198:201], v[82:85]
	v_mfma_f32_16x16x32_bf16 v[70:73], v[146:149], v[206:209], v[70:73]
	v_mfma_f32_16x16x32_bf16 v[66:69], v[154:157], v[206:209], v[66:69]
	v_mfma_f32_16x16x32_bf16 v[134:137], v[150:153], v[186:189], v[134:137]
	v_mfma_f32_16x16x32_bf16 v[130:133], v[158:161], v[186:189], v[130:133]
	v_mfma_f32_16x16x32_bf16 v[118:121], v[150:153], v[194:197], v[118:121]
	v_mfma_f32_16x16x32_bf16 v[114:117], v[158:161], v[194:197], v[114:117]
	v_mfma_f32_16x16x32_bf16 v[86:89], v[150:153], v[202:205], v[86:89]
	v_mfma_f32_16x16x32_bf16 v[82:85], v[158:161], v[202:205], v[82:85]
	v_mfma_f32_16x16x32_bf16 v[70:73], v[150:153], v[218:221], v[70:73]
	v_mfma_f32_16x16x32_bf16 v[66:69], v[158:161], v[218:221], v[66:69]
	s_setprio 0
	s_barrier
	s_add_u32 s98, s34, 0x80
	s_addc_u32 s99, s35, 0
	s_add_u32 s100, s36, 0x80
	s_addc_u32 s101, s37, 0
	s_add_i32 s74, s51, s7
	s_mov_b32 m0, s74
	ds_read_b128 v[182:185], v215 offset:16384
	ds_read_b128 v[186:189], v215 offset:17408
	ds_read_b128 v[190:193], v215 offset:18432
	ds_read_b128 v[194:197], v215 offset:19456
	ds_read_b128 v[198:201], v215 offset:20480
	ds_read_b128 v[202:205], v215 offset:21504
	ds_read_b128 v[206:209], v215 offset:22528
	ds_read_b128 v[218:221], v215 offset:23552
	global_load_lds_dwordx4 v164, s[34:35]
	s_add_i32 m0, s74, 0x2000
	s_add_u32 s74, s34, 0x40000
	s_addc_u32 s75, s35, 0
	s_add_i32 s76, s54, s7
	global_load_lds_dwordx4 v168, s[34:35]
	s_mov_b32 m0, s76
	s_nop 0
	global_load_lds_dwordx4 v164, s[74:75]
	s_add_i32 m0, s76, 0x2000
	s_nop 0
	global_load_lds_dwordx4 v168, s[74:75]
	s_mov_b32 m0, s38
	s_nop 0
	global_load_lds_dwordx4 v162, s[36:37]
	s_mov_b32 m0, s39
	s_nop 0
	global_load_lds_dwordx4 v166, s[36:37]
	s_waitcnt vmcnt(8)
	s_waitcnt lgkmcnt(0)
	s_barrier
	s_setprio 1
	v_mfma_f32_16x16x32_bf16 v[62:65], v[98:101], v[182:185], v[62:65]
	v_mfma_f32_16x16x32_bf16 v[58:61], v[106:109], v[182:185], v[58:61]
	v_mfma_f32_16x16x32_bf16 v[46:49], v[98:101], v[190:193], v[46:49]
	v_mfma_f32_16x16x32_bf16 v[42:45], v[106:109], v[190:193], v[42:45]
	v_mfma_f32_16x16x32_bf16 v[30:33], v[98:101], v[198:201], v[30:33]
	v_mfma_f32_16x16x32_bf16 v[26:29], v[106:109], v[198:201], v[26:29]
	v_mfma_f32_16x16x32_bf16 v[14:17], v[98:101], v[206:209], v[14:17]
	v_mfma_f32_16x16x32_bf16 v[10:13], v[106:109], v[206:209], v[10:13]
	v_mfma_f32_16x16x32_bf16 v[62:65], v[102:105], v[186:189], v[62:65]
	v_mfma_f32_16x16x32_bf16 v[58:61], v[110:113], v[186:189], v[58:61]
	v_mfma_f32_16x16x32_bf16 v[46:49], v[102:105], v[194:197], v[46:49]
	v_mfma_f32_16x16x32_bf16 v[42:45], v[110:113], v[194:197], v[42:45]
	v_mfma_f32_16x16x32_bf16 v[30:33], v[102:105], v[202:205], v[30:33]
	v_mfma_f32_16x16x32_bf16 v[26:29], v[110:113], v[202:205], v[26:29]
	v_mfma_f32_16x16x32_bf16 v[14:17], v[102:105], v[218:221], v[14:17]
	v_mfma_f32_16x16x32_bf16 v[10:13], v[110:113], v[218:221], v[10:13]
	v_mfma_f32_16x16x32_bf16 v[54:57], v[146:149], v[182:185], v[54:57]
	v_mfma_f32_16x16x32_bf16 v[50:53], v[154:157], v[182:185], v[50:53]
	v_mfma_f32_16x16x32_bf16 v[38:41], v[146:149], v[190:193], v[38:41]
	v_mfma_f32_16x16x32_bf16 v[34:37], v[154:157], v[190:193], v[34:37]
	v_mfma_f32_16x16x32_bf16 v[22:25], v[146:149], v[198:201], v[22:25]
	v_mfma_f32_16x16x32_bf16 v[18:21], v[154:157], v[198:201], v[18:21]
	v_mfma_f32_16x16x32_bf16 v[6:9], v[146:149], v[206:209], v[6:9]
	v_mfma_f32_16x16x32_bf16 v[2:5], v[154:157], v[206:209], v[2:5]
	v_mfma_f32_16x16x32_bf16 v[54:57], v[150:153], v[186:189], v[54:57]
	v_mfma_f32_16x16x32_bf16 v[50:53], v[158:161], v[186:189], v[50:53]
	v_mfma_f32_16x16x32_bf16 v[38:41], v[150:153], v[194:197], v[38:41]
	v_mfma_f32_16x16x32_bf16 v[34:37], v[158:161], v[194:197], v[34:37]
	v_mfma_f32_16x16x32_bf16 v[22:25], v[150:153], v[202:205], v[22:25]
	v_mfma_f32_16x16x32_bf16 v[18:21], v[158:161], v[202:205], v[18:21]
	v_mfma_f32_16x16x32_bf16 v[6:9], v[150:153], v[218:221], v[6:9]
	v_mfma_f32_16x16x32_bf16 v[2:5], v[158:161], v[218:221], v[2:5]
	s_setprio 0
	s_barrier
	s_add_i32 s74, 0, 0x18000
	v_add_u32_e32 v1, s74, v173
	s_add_i32 s75, 0, 0x1c000
	ds_read_b128 v[98:101], v1
	ds_read_b128 v[102:105], v1 offset:1024
	ds_read_b128 v[106:109], v1 offset:2048
	ds_read_b128 v[110:113], v1 offset:3072
	v_add_u32_e32 v1, s75, v173
	ds_read_b128 v[146:149], v1
	ds_read_b128 v[150:153], v1 offset:1024
	ds_read_b128 v[154:157], v1 offset:2048
	ds_read_b128 v[158:161], v1 offset:3072
	s_add_u32 s36, s36, 0x40000
	s_addc_u32 s37, s37, 0
	s_mov_b32 m0, s40
	ds_read_b128 v[182:185], v215 offset:32768
	ds_read_b128 v[186:189], v215 offset:33792
	ds_read_b128 v[190:193], v215 offset:34816
	ds_read_b128 v[194:197], v215 offset:35840
	ds_read_b128 v[198:201], v215 offset:36864
	ds_read_b128 v[202:205], v215 offset:37888
	ds_read_b128 v[206:209], v215 offset:38912
	ds_read_b128 v[218:221], v215 offset:39936
	global_load_lds_dwordx4 v162, s[36:37]
	s_mov_b32 m0, s41
	s_nop 0
	global_load_lds_dwordx4 v166, s[36:37]
	s_waitcnt vmcnt(8)
	s_waitcnt lgkmcnt(0)
	s_barrier
	s_setprio 1
	v_mfma_f32_16x16x32_bf16 v[142:145], v[98:101], v[182:185], v[142:145]
	v_mfma_f32_16x16x32_bf16 v[138:141], v[106:109], v[182:185], v[138:141]
	v_mfma_f32_16x16x32_bf16 v[126:129], v[98:101], v[190:193], v[126:129]
	v_mfma_f32_16x16x32_bf16 v[122:125], v[106:109], v[190:193], v[122:125]
	v_mfma_f32_16x16x32_bf16 v[94:97], v[98:101], v[198:201], v[94:97]
	v_mfma_f32_16x16x32_bf16 v[90:93], v[106:109], v[198:201], v[90:93]
	v_mfma_f32_16x16x32_bf16 v[78:81], v[98:101], v[206:209], v[78:81]
	v_mfma_f32_16x16x32_bf16 v[74:77], v[106:109], v[206:209], v[74:77]
	v_mfma_f32_16x16x32_bf16 v[142:145], v[102:105], v[186:189], v[142:145]
	v_mfma_f32_16x16x32_bf16 v[138:141], v[110:113], v[186:189], v[138:141]
	v_mfma_f32_16x16x32_bf16 v[126:129], v[102:105], v[194:197], v[126:129]
	v_mfma_f32_16x16x32_bf16 v[122:125], v[110:113], v[194:197], v[122:125]
	v_mfma_f32_16x16x32_bf16 v[94:97], v[102:105], v[202:205], v[94:97]
	v_mfma_f32_16x16x32_bf16 v[90:93], v[110:113], v[202:205], v[90:93]
	v_mfma_f32_16x16x32_bf16 v[78:81], v[102:105], v[218:221], v[78:81]
	v_mfma_f32_16x16x32_bf16 v[74:77], v[110:113], v[218:221], v[74:77]
	v_mfma_f32_16x16x32_bf16 v[134:137], v[146:149], v[182:185], v[134:137]
	v_mfma_f32_16x16x32_bf16 v[130:133], v[154:157], v[182:185], v[130:133]
	v_mfma_f32_16x16x32_bf16 v[118:121], v[146:149], v[190:193], v[118:121]
	v_mfma_f32_16x16x32_bf16 v[114:117], v[154:157], v[190:193], v[114:117]
	v_mfma_f32_16x16x32_bf16 v[86:89], v[146:149], v[198:201], v[86:89]
	v_mfma_f32_16x16x32_bf16 v[82:85], v[154:157], v[198:201], v[82:85]
	v_mfma_f32_16x16x32_bf16 v[70:73], v[146:149], v[206:209], v[70:73]
	v_mfma_f32_16x16x32_bf16 v[66:69], v[154:157], v[206:209], v[66:69]
	v_mfma_f32_16x16x32_bf16 v[134:137], v[150:153], v[186:189], v[134:137]
	v_mfma_f32_16x16x32_bf16 v[130:133], v[158:161], v[186:189], v[130:133]
	v_mfma_f32_16x16x32_bf16 v[118:121], v[150:153], v[194:197], v[118:121]
	v_mfma_f32_16x16x32_bf16 v[114:117], v[158:161], v[194:197], v[114:117]
	v_mfma_f32_16x16x32_bf16 v[86:89], v[150:153], v[202:205], v[86:89]
	v_mfma_f32_16x16x32_bf16 v[82:85], v[158:161], v[202:205], v[82:85]
	v_mfma_f32_16x16x32_bf16 v[70:73], v[150:153], v[218:221], v[70:73]
	v_mfma_f32_16x16x32_bf16 v[66:69], v[158:161], v[218:221], v[66:69]
	s_setprio 0
	s_barrier
	s_add_i32 s36, s74, s7
	s_mov_b32 m0, s36
	ds_read_b128 v[182:185], v215 offset:49152
	ds_read_b128 v[186:189], v215 offset:50176
	ds_read_b128 v[190:193], v215 offset:51200
	ds_read_b128 v[194:197], v215 offset:52224
	ds_read_b128 v[198:201], v215 offset:53248
	ds_read_b128 v[202:205], v215 offset:54272
	ds_read_b128 v[206:209], v215 offset:55296
	ds_read_b128 v[218:221], v215 offset:56320
	global_load_lds_dwordx4 v164, s[98:99]
	s_add_i32 m0, s36, 0x2000
	s_add_u32 s34, s34, 0x40080
	s_addc_u32 s35, s35, 0
	s_add_i32 s36, s75, s7
	global_load_lds_dwordx4 v168, s[98:99]
	s_mov_b32 m0, s36
	s_nop 0
	global_load_lds_dwordx4 v164, s[34:35]
	s_add_i32 m0, s36, 0x2000
	s_nop 0
	global_load_lds_dwordx4 v168, s[34:35]
	s_mov_b32 m0, s47
	s_nop 0
	global_load_lds_dwordx4 v162, s[100:101]
	s_mov_b32 m0, s48
	s_nop 0
	global_load_lds_dwordx4 v166, s[100:101]
	s_waitcnt vmcnt(8)
	s_waitcnt lgkmcnt(0)
	s_barrier
	s_setprio 1
	v_mfma_f32_16x16x32_bf16 v[62:65], v[98:101], v[182:185], v[62:65]
	v_mfma_f32_16x16x32_bf16 v[58:61], v[106:109], v[182:185], v[58:61]
	v_mfma_f32_16x16x32_bf16 v[46:49], v[98:101], v[190:193], v[46:49]
	v_mfma_f32_16x16x32_bf16 v[42:45], v[106:109], v[190:193], v[42:45]
	v_mfma_f32_16x16x32_bf16 v[30:33], v[98:101], v[198:201], v[30:33]
	v_mfma_f32_16x16x32_bf16 v[26:29], v[106:109], v[198:201], v[26:29]
	v_mfma_f32_16x16x32_bf16 v[14:17], v[98:101], v[206:209], v[14:17]
	v_mfma_f32_16x16x32_bf16 v[10:13], v[106:109], v[206:209], v[10:13]
	v_mfma_f32_16x16x32_bf16 v[62:65], v[102:105], v[186:189], v[62:65]
	v_mfma_f32_16x16x32_bf16 v[58:61], v[110:113], v[186:189], v[58:61]
	v_mfma_f32_16x16x32_bf16 v[46:49], v[102:105], v[194:197], v[46:49]
	v_mfma_f32_16x16x32_bf16 v[42:45], v[110:113], v[194:197], v[42:45]
	v_mfma_f32_16x16x32_bf16 v[30:33], v[102:105], v[202:205], v[30:33]
	v_mfma_f32_16x16x32_bf16 v[26:29], v[110:113], v[202:205], v[26:29]
	v_mfma_f32_16x16x32_bf16 v[14:17], v[102:105], v[218:221], v[14:17]
	v_mfma_f32_16x16x32_bf16 v[10:13], v[110:113], v[218:221], v[10:13]
	v_mfma_f32_16x16x32_bf16 v[54:57], v[146:149], v[182:185], v[54:57]
	v_mfma_f32_16x16x32_bf16 v[50:53], v[154:157], v[182:185], v[50:53]
	v_mfma_f32_16x16x32_bf16 v[38:41], v[146:149], v[190:193], v[38:41]
	v_mfma_f32_16x16x32_bf16 v[34:37], v[154:157], v[190:193], v[34:37]
	v_mfma_f32_16x16x32_bf16 v[22:25], v[146:149], v[198:201], v[22:25]
	v_mfma_f32_16x16x32_bf16 v[18:21], v[154:157], v[198:201], v[18:21]
	v_mfma_f32_16x16x32_bf16 v[6:9], v[146:149], v[206:209], v[6:9]
	v_mfma_f32_16x16x32_bf16 v[2:5], v[154:157], v[206:209], v[2:5]
	v_mfma_f32_16x16x32_bf16 v[54:57], v[150:153], v[186:189], v[54:57]
	v_mfma_f32_16x16x32_bf16 v[50:53], v[158:161], v[186:189], v[50:53]
	v_mfma_f32_16x16x32_bf16 v[38:41], v[150:153], v[194:197], v[38:41]
	v_mfma_f32_16x16x32_bf16 v[34:37], v[158:161], v[194:197], v[34:37]
	v_mfma_f32_16x16x32_bf16 v[22:25], v[150:153], v[202:205], v[22:25]
	v_mfma_f32_16x16x32_bf16 v[18:21], v[158:161], v[202:205], v[18:21]
	v_mfma_f32_16x16x32_bf16 v[6:9], v[150:153], v[218:221], v[6:9]
	v_mfma_f32_16x16x32_bf16 v[2:5], v[158:161], v[218:221], v[2:5]
	s_setprio 0
	s_barrier
	s_add_i32 s71, s71, 2
	s_add_u32 s30, s30, 0x100
	s_addc_u32 s31, s31, 0
	s_add_u32 s55, s55, 0x100
	s_addc_u32 s70, s70, 0
	s_cmp_gt_u32 s71, 13
	s_cbranch_scc0 .LBB0_450
	s_and_b64 vcc, exec, s[16:17]
	s_cbranch_vccz .LBB0_453
	s_barrier

.Lei_4:
	s_barrier
	s_mov_b64 s[4:5], exec
	v_readlane_b32 s6, v255, 4
	v_readlane_b32 s7, v255, 5
	s_and_b64 s[6:7], s[4:5], s[6:7]
	s_mov_b64 exec, s[6:7]
	s_cbranch_execz .LBB0_539
	s_add_i32 s3, 0, 0x22020
	v_mov_b32_e32 v1, s3
	s_waitcnt lgkmcnt(0)
	ds_read_b32 v4, v1
	s_add_i32 s3, 0, 0x22024
	v_mov_b32_e32 v1, s3
	ds_read_b32 v2, v1
	s_waitcnt lgkmcnt(1)
	v_cmp_ne_u32_e32 vcc, 0, v4
	s_cbranch_vccnz .LBB0_503
	v_readlane_b32 s8, v255, 1
	v_readlane_b32 s9, v255, 2
	s_load_dwordx2 s[6:7], s[8:9], 0x4
	s_add_u32 s8, s88, 0x1200
	s_addc_u32 s9, s89, 0
	s_add_u32 s12, s88, 0x1400
	s_addc_u32 s13, s89, 0
	s_add_u32 s14, s88, 0x1500
	s_addc_u32 s15, s89, 0
	s_add_u32 s16, s88, 0x1600
	s_addc_u32 s17, s89, 0
	s_add_u32 s18, s88, 0x1700
	s_addc_u32 s19, s89, 0
	s_add_u32 s20, s88, 0x1800
	s_addc_u32 s21, s89, 0
	s_add_u32 s22, s88, 0x1900
	s_addc_u32 s23, s89, 0
	s_add_u32 s24, s88, 0x1a00
	s_addc_u32 s25, s89, 0
	s_add_u32 s26, s88, 0x1b00
	s_addc_u32 s27, s89, 0
	s_add_u32 s28, s88, 0x1c00
	s_addc_u32 s29, s89, 0
	s_add_u32 s30, s88, 0x1d00
	s_addc_u32 s31, s89, 0
	s_add_u32 s34, s88, 0x1e00
	s_addc_u32 s35, s89, 0
	s_add_u32 s36, s88, 0x1f00
	s_addc_u32 s37, s89, 0
	s_add_u32 s38, s88, 0x2000
	s_addc_u32 s39, s89, 0
	s_add_u32 s40, s88, 0x2100
	s_addc_u32 s41, s89, 0
	s_add_u32 s42, s88, 0x2200
	s_addc_u32 s43, s89, 0
	s_waitcnt lgkmcnt(0)
	s_mul_i32 s3, s6, s33
	s_add_u32 s44, s88, 0x2300
	s_mul_i32 s3, s3, s7
	s_addc_u32 s45, s89, 0
	s_mov_b32 s6, 1
	v_mov_b32_e32 v18, 0
	s_branch .LBB0_491

.LBB0_536:
	s_or_b64 exec, exec, s[12:13]
	s_mov_b64 s[12:13], exec
	v_mbcnt_lo_u32_b32 v1, s12, 0
	v_mbcnt_hi_u32_b32 v1, s13, v1
	v_cmp_eq_u32_e32 vcc, 0, v1
	s_waitcnt vmcnt(0)
	s_and_saveexec_b64 s[14:15], vcc
	s_cbranch_execz .LBB0_538
	s_bcnt1_i32_b64 s3, s[12:13]
	v_mov_b32_e32 v1, 0x2000
	v_mov_b32_e32 v2, s3
	global_atomic_add v1, v2, s[8:9] offset:1024

.LBB0_557:
	ds_read_b128 v[30:33], v219
	ds_read_b128 v[54:57], v219 offset:1024
	ds_read_b128 v[118:121], v219 offset:2048
	ds_read_b128 v[122:125], v219 offset:3072
	ds_read_b128 v[146:149], v220
	ds_read_b128 v[150:153], v220 offset:1024
	ds_read_b128 v[154:157], v220 offset:2048
	ds_read_b128 v[158:161], v220 offset:3072
	s_add_u32 s48, s8, 0xfffc0080
	s_addc_u32 s49, s9, -1
	s_cmp_eq_u32 s7, 12
	s_cselect_b32 s51, s41, s49
	s_cselect_b32 s50, s47, s48
	s_cselect_b32 s49, s39, s3
	s_cselect_b32 s48, vcc_lo, vcc_hi
	s_add_i32 m0, s70, 0xc000
	ds_read_b128 v[162:165], v221
	ds_read_b128 v[166:169], v221 offset:1024
	ds_read_b128 v[194:197], v221 offset:2048
	ds_read_b128 v[198:201], v221 offset:3072
	ds_read_b128 v[202:205], v221 offset:4096
	ds_read_b128 v[206:209], v221 offset:5120
	ds_read_b128 v[224:227], v221 offset:6144
	ds_read_b128 v[228:231], v221 offset:7168
	global_load_lds_dwordx4 v186, s[8:9]
	s_add_i32 m0, s70, 0xe000
	s_nop 0
	global_load_lds_dwordx4 v188, s[8:9]
	s_waitcnt vmcnt(8)
	s_waitcnt lgkmcnt(0)
	s_barrier
	s_setprio 1
	v_mfma_f32_16x16x32_bf16 v[62:65], v[30:33], v[162:165], v[62:65]
	v_mfma_f32_16x16x32_bf16 v[42:45], v[118:121], v[162:165], v[42:45]
	v_mfma_f32_16x16x32_bf16 v[50:53], v[30:33], v[194:197], v[50:53]
	v_mfma_f32_16x16x32_bf16 v[38:41], v[118:121], v[194:197], v[38:41]
	v_mfma_f32_16x16x32_bf16 v[46:49], v[30:33], v[202:205], v[46:49]
	v_mfma_f32_16x16x32_bf16 v[34:37], v[118:121], v[202:205], v[34:37]
	v_mfma_f32_16x16x32_bf16 v[142:145], v[30:33], v[224:227], v[142:145]
	v_mfma_f32_16x16x32_bf16 v[82:85], v[118:121], v[224:227], v[82:85]
	v_mfma_f32_16x16x32_bf16 v[62:65], v[54:57], v[166:169], v[62:65]
	v_mfma_f32_16x16x32_bf16 v[42:45], v[122:125], v[166:169], v[42:45]
	v_mfma_f32_16x16x32_bf16 v[50:53], v[54:57], v[198:201], v[50:53]
	v_mfma_f32_16x16x32_bf16 v[38:41], v[122:125], v[198:201], v[38:41]
	v_mfma_f32_16x16x32_bf16 v[46:49], v[54:57], v[206:209], v[46:49]
	v_mfma_f32_16x16x32_bf16 v[34:37], v[122:125], v[206:209], v[34:37]
	v_mfma_f32_16x16x32_bf16 v[142:145], v[54:57], v[228:231], v[142:145]
	v_mfma_f32_16x16x32_bf16 v[82:85], v[122:125], v[228:231], v[82:85]
	v_mfma_f32_16x16x32_bf16 v[134:137], v[146:149], v[162:165], v[134:137]
	v_mfma_f32_16x16x32_bf16 v[74:77], v[154:157], v[162:165], v[74:77]
	v_mfma_f32_16x16x32_bf16 v[130:133], v[146:149], v[194:197], v[130:133]
	v_mfma_f32_16x16x32_bf16 v[70:73], v[154:157], v[194:197], v[70:73]
	v_mfma_f32_16x16x32_bf16 v[78:81], v[146:149], v[202:205], v[78:81]
	v_mfma_f32_16x16x32_bf16 v[66:69], v[154:157], v[202:205], v[66:69]
	v_mfma_f32_16x16x32_bf16 v[138:141], v[146:149], v[224:227], v[138:141]
	v_mfma_f32_16x16x32_bf16 v[98:101], v[154:157], v[224:227], v[98:101]
	v_mfma_f32_16x16x32_bf16 v[134:137], v[150:153], v[166:169], v[134:137]
	v_mfma_f32_16x16x32_bf16 v[74:77], v[158:161], v[166:169], v[74:77]
	v_mfma_f32_16x16x32_bf16 v[130:133], v[150:153], v[198:201], v[130:133]
	v_mfma_f32_16x16x32_bf16 v[70:73], v[158:161], v[198:201], v[70:73]
	v_mfma_f32_16x16x32_bf16 v[78:81], v[150:153], v[206:209], v[78:81]
	v_mfma_f32_16x16x32_bf16 v[66:69], v[158:161], v[206:209], v[66:69]
	v_mfma_f32_16x16x32_bf16 v[138:141], v[150:153], v[228:231], v[138:141]
	v_mfma_f32_16x16x32_bf16 v[98:101], v[158:161], v[228:231], v[98:101]
	s_setprio 0
	s_barrier
	s_add_u32 s98, s48, 0x80
	s_addc_u32 s99, s49, 0
	s_add_u32 s100, s50, 0x80
	s_addc_u32 s101, s51, 0
	s_add_i32 s84, s93, s64
	s_mov_b32 m0, s84
	ds_read_b128 v[162:165], v221 offset:16384
	ds_read_b128 v[166:169], v221 offset:17408
	ds_read_b128 v[194:197], v221 offset:18432
	ds_read_b128 v[198:201], v221 offset:19456
	ds_read_b128 v[202:205], v221 offset:20480
	ds_read_b128 v[206:209], v221 offset:21504
	ds_read_b128 v[224:227], v221 offset:22528
	ds_read_b128 v[228:231], v221 offset:23552
	global_load_lds_dwordx4 v176, s[48:49]
	s_add_i32 m0, s84, 0x2000
	s_add_u32 s84, s48, 0x40000
	s_addc_u32 s85, s49, 0
	s_add_i32 s86, s90, s64
	global_load_lds_dwordx4 v180, s[48:49]
	s_mov_b32 m0, s86
	s_nop 0
	global_load_lds_dwordx4 v176, s[84:85]
	s_add_i32 m0, s86, 0x2000
	s_nop 0
	global_load_lds_dwordx4 v180, s[84:85]
	s_mov_b32 m0, s70
	s_nop 0
	global_load_lds_dwordx4 v174, s[50:51]
	s_mov_b32 m0, s71
	s_nop 0
	global_load_lds_dwordx4 v178, s[50:51]
	s_waitcnt vmcnt(8)
	s_waitcnt lgkmcnt(0)
	s_barrier
	s_setprio 1
	v_mfma_f32_16x16x32_bf16 v[94:97], v[30:33], v[162:165], v[94:97]
	v_mfma_f32_16x16x32_bf16 v[10:13], v[118:121], v[162:165], v[10:13]
	v_mfma_f32_16x16x32_bf16 v[90:93], v[30:33], v[194:197], v[90:93]
	v_mfma_f32_16x16x32_bf16 v[6:9], v[118:121], v[194:197], v[6:9]
	v_mfma_f32_16x16x32_bf16 v[86:89], v[30:33], v[202:205], v[86:89]
	v_mfma_f32_16x16x32_bf16 v[2:5], v[118:121], v[202:205], v[2:5]
	v_mfma_f32_16x16x32_bf16 v[26:29], v[118:121], v[224:227], v[26:29]
	v_mfma_f32_16x16x32_bf16 v[94:97], v[54:57], v[166:169], v[94:97]
	v_mfma_f32_16x16x32_bf16 v[10:13], v[122:125], v[166:169], v[10:13]
	v_mfma_f32_16x16x32_bf16 v[90:93], v[54:57], v[198:201], v[90:93]
	v_mfma_f32_16x16x32_bf16 v[6:9], v[122:125], v[198:201], v[6:9]
	v_mfma_f32_16x16x32_bf16 v[86:89], v[54:57], v[206:209], v[86:89]
	v_mfma_f32_16x16x32_bf16 v[2:5], v[122:125], v[206:209], v[2:5]
	v_mfma_f32_16x16x32_bf16 v[30:33], v[30:33], v[224:227], v[114:117]
	v_mfma_f32_16x16x32_bf16 v[26:29], v[122:125], v[228:231], v[26:29]
	v_mfma_f32_16x16x32_bf16 v[30:33], v[54:57], v[228:231], v[30:33]
	v_mfma_f32_16x16x32_bf16 v[22:25], v[154:157], v[162:165], v[22:25]
	v_mfma_f32_16x16x32_bf16 v[106:109], v[146:149], v[194:197], v[106:109]
	v_mfma_f32_16x16x32_bf16 v[18:21], v[154:157], v[194:197], v[18:21]
	v_mfma_f32_16x16x32_bf16 v[102:105], v[146:149], v[202:205], v[102:105]
	v_mfma_f32_16x16x32_bf16 v[14:17], v[154:157], v[202:205], v[14:17]
	v_mfma_f32_16x16x32_bf16 v[58:61], v[154:157], v[224:227], v[58:61]
	v_mfma_f32_16x16x32_bf16 v[54:57], v[146:149], v[162:165], v[110:113]
	v_mfma_f32_16x16x32_bf16 v[22:25], v[158:161], v[166:169], v[22:25]
	v_mfma_f32_16x16x32_bf16 v[106:109], v[150:153], v[198:201], v[106:109]
	v_mfma_f32_16x16x32_bf16 v[18:21], v[158:161], v[198:201], v[18:21]
	v_mfma_f32_16x16x32_bf16 v[102:105], v[150:153], v[206:209], v[102:105]
	v_mfma_f32_16x16x32_bf16 v[14:17], v[158:161], v[206:209], v[14:17]
	v_mfma_f32_16x16x32_bf16 v[110:113], v[146:149], v[224:227], v[126:129]
	v_mfma_f32_16x16x32_bf16 v[58:61], v[158:161], v[228:231], v[58:61]
	v_mfma_f32_16x16x32_bf16 v[54:57], v[150:153], v[166:169], v[54:57]
	v_mfma_f32_16x16x32_bf16 v[118:121], v[150:153], v[228:231], v[110:113]
	s_setprio 0
	s_barrier
	s_add_i32 s84, 0, 0x18000
	v_add_u32_e32 v1, s84, v210
	s_add_i32 s85, 0, 0x1c000
	ds_read_b128 v[110:113], v1
	ds_read_b128 v[114:117], v1 offset:1024
	ds_read_b128 v[122:125], v1 offset:2048
	ds_read_b128 v[126:129], v1 offset:3072
	v_add_u32_e32 v1, s85, v210
	ds_read_b128 v[146:149], v1
	ds_read_b128 v[150:153], v1 offset:1024
	ds_read_b128 v[154:157], v1 offset:2048
	ds_read_b128 v[158:161], v1 offset:3072
	s_add_u32 s50, s50, 0x40000
	s_addc_u32 s51, s51, 0
	s_mov_b32 m0, s74
	ds_read_b128 v[162:165], v221 offset:32768
	ds_read_b128 v[166:169], v221 offset:33792
	ds_read_b128 v[194:197], v221 offset:34816
	ds_read_b128 v[198:201], v221 offset:35840
	ds_read_b128 v[202:205], v221 offset:36864
	ds_read_b128 v[206:209], v221 offset:37888
	ds_read_b128 v[224:227], v221 offset:38912
	ds_read_b128 v[228:231], v221 offset:39936
	global_load_lds_dwordx4 v174, s[50:51]
	s_mov_b32 m0, s75
	s_nop 0
	global_load_lds_dwordx4 v178, s[50:51]
	s_waitcnt vmcnt(8)
	s_waitcnt lgkmcnt(0)
	s_barrier
	s_setprio 1
	v_mfma_f32_16x16x32_bf16 v[62:65], v[110:113], v[162:165], v[62:65]
	v_mfma_f32_16x16x32_bf16 v[42:45], v[122:125], v[162:165], v[42:45]
	v_mfma_f32_16x16x32_bf16 v[50:53], v[110:113], v[194:197], v[50:53]
	v_mfma_f32_16x16x32_bf16 v[38:41], v[122:125], v[194:197], v[38:41]
	v_mfma_f32_16x16x32_bf16 v[46:49], v[110:113], v[202:205], v[46:49]
	v_mfma_f32_16x16x32_bf16 v[34:37], v[122:125], v[202:205], v[34:37]
	v_mfma_f32_16x16x32_bf16 v[142:145], v[110:113], v[224:227], v[142:145]
	v_mfma_f32_16x16x32_bf16 v[82:85], v[122:125], v[224:227], v[82:85]
	v_mfma_f32_16x16x32_bf16 v[62:65], v[114:117], v[166:169], v[62:65]
	v_mfma_f32_16x16x32_bf16 v[42:45], v[126:129], v[166:169], v[42:45]
	v_mfma_f32_16x16x32_bf16 v[50:53], v[114:117], v[198:201], v[50:53]
	v_mfma_f32_16x16x32_bf16 v[38:41], v[126:129], v[198:201], v[38:41]
	v_mfma_f32_16x16x32_bf16 v[46:49], v[114:117], v[206:209], v[46:49]
	v_mfma_f32_16x16x32_bf16 v[34:37], v[126:129], v[206:209], v[34:37]
	v_mfma_f32_16x16x32_bf16 v[142:145], v[114:117], v[228:231], v[142:145]
	v_mfma_f32_16x16x32_bf16 v[82:85], v[126:129], v[228:231], v[82:85]
	v_mfma_f32_16x16x32_bf16 v[134:137], v[146:149], v[162:165], v[134:137]
	v_mfma_f32_16x16x32_bf16 v[74:77], v[154:157], v[162:165], v[74:77]
	v_mfma_f32_16x16x32_bf16 v[130:133], v[146:149], v[194:197], v[130:133]
	v_mfma_f32_16x16x32_bf16 v[70:73], v[154:157], v[194:197], v[70:73]
	v_mfma_f32_16x16x32_bf16 v[78:81], v[146:149], v[202:205], v[78:81]
	v_mfma_f32_16x16x32_bf16 v[66:69], v[154:157], v[202:205], v[66:69]
	v_mfma_f32_16x16x32_bf16 v[138:141], v[146:149], v[224:227], v[138:141]
	v_mfma_f32_16x16x32_bf16 v[98:101], v[154:157], v[224:227], v[98:101]
	v_mfma_f32_16x16x32_bf16 v[134:137], v[150:153], v[166:169], v[134:137]
	v_mfma_f32_16x16x32_bf16 v[74:77], v[158:161], v[166:169], v[74:77]
	v_mfma_f32_16x16x32_bf16 v[130:133], v[150:153], v[198:201], v[130:133]
	v_mfma_f32_16x16x32_bf16 v[70:73], v[158:161], v[198:201], v[70:73]
	v_mfma_f32_16x16x32_bf16 v[78:81], v[150:153], v[206:209], v[78:81]
	v_mfma_f32_16x16x32_bf16 v[66:69], v[158:161], v[206:209], v[66:69]
	v_mfma_f32_16x16x32_bf16 v[138:141], v[150:153], v[228:231], v[138:141]
	v_mfma_f32_16x16x32_bf16 v[98:101], v[158:161], v[228:231], v[98:101]
	s_setprio 0
	s_barrier
	s_add_i32 s50, s84, s64
	s_mov_b32 m0, s50
	ds_read_b128 v[162:165], v221 offset:49152
	ds_read_b128 v[166:169], v221 offset:50176
	ds_read_b128 v[194:197], v221 offset:51200
	ds_read_b128 v[198:201], v221 offset:52224
	ds_read_b128 v[202:205], v221 offset:53248
	ds_read_b128 v[206:209], v221 offset:54272
	ds_read_b128 v[224:227], v221 offset:55296
	ds_read_b128 v[228:231], v221 offset:56320
	global_load_lds_dwordx4 v176, s[98:99]
	s_add_i32 m0, s50, 0x2000
	s_add_u32 s48, s48, 0x40080
	s_addc_u32 s49, s49, 0
	s_add_i32 s50, s85, s64
	global_load_lds_dwordx4 v180, s[98:99]
	s_mov_b32 m0, s50
	s_nop 0
	global_load_lds_dwordx4 v176, s[48:49]
	s_add_i32 m0, s50, 0x2000
	s_nop 0
	global_load_lds_dwordx4 v180, s[48:49]
	s_mov_b32 m0, s77
	s_nop 0
	global_load_lds_dwordx4 v174, s[100:101]
	s_mov_b32 m0, s78
	s_nop 0
	global_load_lds_dwordx4 v178, s[100:101]
	s_waitcnt vmcnt(8)
	s_waitcnt lgkmcnt(0)
	s_barrier
	s_setprio 1
	v_mfma_f32_16x16x32_bf16 v[94:97], v[110:113], v[162:165], v[94:97]
	v_mfma_f32_16x16x32_bf16 v[10:13], v[122:125], v[162:165], v[10:13]
	v_mfma_f32_16x16x32_bf16 v[90:93], v[110:113], v[194:197], v[90:93]
	v_mfma_f32_16x16x32_bf16 v[6:9], v[122:125], v[194:197], v[6:9]
	v_mfma_f32_16x16x32_bf16 v[86:89], v[110:113], v[202:205], v[86:89]
	v_mfma_f32_16x16x32_bf16 v[2:5], v[122:125], v[202:205], v[2:5]
	v_mfma_f32_16x16x32_bf16 v[30:33], v[110:113], v[224:227], v[30:33]
	v_mfma_f32_16x16x32_bf16 v[26:29], v[122:125], v[224:227], v[26:29]
	v_mfma_f32_16x16x32_bf16 v[94:97], v[114:117], v[166:169], v[94:97]
	v_mfma_f32_16x16x32_bf16 v[10:13], v[126:129], v[166:169], v[10:13]
	v_mfma_f32_16x16x32_bf16 v[90:93], v[114:117], v[198:201], v[90:93]
	v_mfma_f32_16x16x32_bf16 v[6:9], v[126:129], v[198:201], v[6:9]
	v_mfma_f32_16x16x32_bf16 v[86:89], v[114:117], v[206:209], v[86:89]
	v_mfma_f32_16x16x32_bf16 v[2:5], v[126:129], v[206:209], v[2:5]
	v_mfma_f32_16x16x32_bf16 v[114:117], v[114:117], v[228:231], v[30:33]
	v_mfma_f32_16x16x32_bf16 v[26:29], v[126:129], v[228:231], v[26:29]
	v_mfma_f32_16x16x32_bf16 v[30:33], v[146:149], v[162:165], v[54:57]
	v_mfma_f32_16x16x32_bf16 v[110:113], v[150:153], v[166:169], v[30:33]
	v_mfma_f32_16x16x32_bf16 v[30:33], v[146:149], v[194:197], v[106:109]
	v_mfma_f32_16x16x32_bf16 v[106:109], v[150:153], v[198:201], v[30:33]
	v_mfma_f32_16x16x32_bf16 v[30:33], v[146:149], v[202:205], v[102:105]
	v_mfma_f32_16x16x32_bf16 v[102:105], v[150:153], v[206:209], v[30:33]
	v_mfma_f32_16x16x32_bf16 v[30:33], v[146:149], v[224:227], v[118:121]
	v_mfma_f32_16x16x32_bf16 v[22:25], v[154:157], v[162:165], v[22:25]
	v_mfma_f32_16x16x32_bf16 v[18:21], v[154:157], v[194:197], v[18:21]
	v_mfma_f32_16x16x32_bf16 v[14:17], v[154:157], v[202:205], v[14:17]
	v_mfma_f32_16x16x32_bf16 v[126:129], v[150:153], v[228:231], v[30:33]
	v_mfma_f32_16x16x32_bf16 v[30:33], v[154:157], v[224:227], v[58:61]
	v_mfma_f32_16x16x32_bf16 v[22:25], v[158:161], v[166:169], v[22:25]
	v_mfma_f32_16x16x32_bf16 v[18:21], v[158:161], v[198:201], v[18:21]
	v_mfma_f32_16x16x32_bf16 v[14:17], v[158:161], v[206:209], v[14:17]
	v_mfma_f32_16x16x32_bf16 v[58:61], v[158:161], v[228:231], v[30:33]
	s_setprio 0
	s_barrier
	s_add_i32 s7, s7, 2
	s_add_u32 s8, s8, 0x100
	s_addc_u32 s9, s9, 0
	s_add_u32 vcc_hi, vcc_hi, 0x100
	s_addc_u32 s3, s3, 0
	s_cmp_gt_u32 s7, 13
	s_cbranch_scc0 .LBB0_557
	s_and_b64 vcc, exec, s[14:15]
	s_cbranch_vccz .LBB0_560
	s_barrier

.LBB0_733:
	ds_read_b128 v[78:81], v184
	ds_read_b128 v[86:89], v184 offset:1024
	ds_read_b128 v[90:93], v184 offset:2048
	ds_read_b128 v[94:97], v184 offset:3072
	ds_read_b128 v[146:149], v185
	ds_read_b128 v[150:153], v185 offset:1024
	ds_read_b128 v[176:179], v185 offset:2048
	ds_read_b128 v[180:183], v185 offset:3072
	s_add_u32 s26, s24, 0xfff50080
	s_addc_u32 s27, s25, -1
	s_cmp_eq_u32 s51, 40
	s_cselect_b32 s29, s9, s27
	s_cselect_b32 s28, s8, s26
	s_cselect_b32 s27, s23, s50
	s_cselect_b32 s26, s22, s49
	s_add_i32 m0, s34, 0xc000
	ds_read_b128 v[188:191], v186
	ds_read_b128 v[192:195], v186 offset:1024
	ds_read_b128 v[196:199], v186 offset:2048
	ds_read_b128 v[200:203], v186 offset:3072
	ds_read_b128 v[204:207], v186 offset:4096
	ds_read_b128 v[208:211], v186 offset:5120
	ds_read_b128 v[212:215], v186 offset:6144
	ds_read_b128 v[216:219], v186 offset:7168
	global_load_lds_dwordx4 v162, s[24:25]
	s_add_i32 m0, s34, 0xe000
	s_nop 0
	global_load_lds_dwordx4 v164, s[24:25]
	s_waitcnt vmcnt(8)
	s_waitcnt lgkmcnt(0)
	s_barrier
	s_setprio 1
	v_mfma_f32_16x16x32_bf16 v[142:145], v[78:81], v[188:191], v[142:145]
	v_mfma_f32_16x16x32_bf16 v[138:141], v[90:93], v[188:191], v[138:141]
	v_mfma_f32_16x16x32_bf16 v[126:129], v[78:81], v[196:199], v[126:129]
	v_mfma_f32_16x16x32_bf16 v[122:125], v[90:93], v[196:199], v[122:125]
	v_mfma_f32_16x16x32_bf16 v[110:113], v[78:81], v[204:207], v[110:113]
	v_mfma_f32_16x16x32_bf16 v[106:109], v[90:93], v[204:207], v[106:109]
	v_mfma_f32_16x16x32_bf16 v[82:85], v[78:81], v[212:215], v[82:85]
	v_mfma_f32_16x16x32_bf16 v[74:77], v[90:93], v[212:215], v[74:77]
	v_mfma_f32_16x16x32_bf16 v[142:145], v[86:89], v[192:195], v[142:145]
	v_mfma_f32_16x16x32_bf16 v[138:141], v[94:97], v[192:195], v[138:141]
	v_mfma_f32_16x16x32_bf16 v[126:129], v[86:89], v[200:203], v[126:129]
	v_mfma_f32_16x16x32_bf16 v[122:125], v[94:97], v[200:203], v[122:125]
	v_mfma_f32_16x16x32_bf16 v[110:113], v[86:89], v[208:211], v[110:113]
	v_mfma_f32_16x16x32_bf16 v[106:109], v[94:97], v[208:211], v[106:109]
	v_mfma_f32_16x16x32_bf16 v[82:85], v[86:89], v[216:219], v[82:85]
	v_mfma_f32_16x16x32_bf16 v[74:77], v[94:97], v[216:219], v[74:77]
	v_mfma_f32_16x16x32_bf16 v[134:137], v[146:149], v[188:191], v[134:137]
	v_mfma_f32_16x16x32_bf16 v[130:133], v[176:179], v[188:191], v[130:133]
	v_mfma_f32_16x16x32_bf16 v[118:121], v[146:149], v[196:199], v[118:121]
	v_mfma_f32_16x16x32_bf16 v[114:117], v[176:179], v[196:199], v[114:117]
	v_mfma_f32_16x16x32_bf16 v[102:105], v[146:149], v[204:207], v[102:105]
	v_mfma_f32_16x16x32_bf16 v[98:101], v[176:179], v[204:207], v[98:101]
	v_mfma_f32_16x16x32_bf16 v[70:73], v[146:149], v[212:215], v[70:73]
	v_mfma_f32_16x16x32_bf16 v[66:69], v[176:179], v[212:215], v[66:69]
	v_mfma_f32_16x16x32_bf16 v[134:137], v[150:153], v[192:195], v[134:137]
	v_mfma_f32_16x16x32_bf16 v[130:133], v[180:183], v[192:195], v[130:133]
	v_mfma_f32_16x16x32_bf16 v[118:121], v[150:153], v[200:203], v[118:121]
	v_mfma_f32_16x16x32_bf16 v[114:117], v[180:183], v[200:203], v[114:117]
	v_mfma_f32_16x16x32_bf16 v[102:105], v[150:153], v[208:211], v[102:105]
	v_mfma_f32_16x16x32_bf16 v[98:101], v[180:183], v[208:211], v[98:101]
	v_mfma_f32_16x16x32_bf16 v[70:73], v[150:153], v[216:219], v[70:73]
	v_mfma_f32_16x16x32_bf16 v[66:69], v[180:183], v[216:219], v[66:69]
	s_setprio 0
	s_barrier
	s_add_u32 s98, s26, 0x80
	s_addc_u32 s99, s27, 0
	s_add_u32 s100, s28, 0x80
	s_addc_u32 s101, s29, 0
	s_add_i32 s54, s43, s31
	s_mov_b32 m0, s54
	ds_read_b128 v[188:191], v186 offset:16384
	ds_read_b128 v[192:195], v186 offset:17408
	ds_read_b128 v[196:199], v186 offset:18432
	ds_read_b128 v[200:203], v186 offset:19456
	ds_read_b128 v[204:207], v186 offset:20480
	ds_read_b128 v[208:211], v186 offset:21504
	ds_read_b128 v[212:215], v186 offset:22528
	ds_read_b128 v[216:219], v186 offset:23552
	global_load_lds_dwordx4 v156, s[26:27]
	s_add_i32 m0, s54, 0x2000
	s_add_u32 s54, s26, 0xb0000
	s_addc_u32 s55, s27, 0
	s_add_i32 s58, s44, s31
	global_load_lds_dwordx4 v160, s[26:27]
	s_mov_b32 m0, s58
	s_nop 0
	global_load_lds_dwordx4 v156, s[54:55]
	s_add_i32 m0, s58, 0x2000
	s_nop 0
	global_load_lds_dwordx4 v160, s[54:55]
	s_mov_b32 m0, s34
	s_nop 0
	global_load_lds_dwordx4 v154, s[28:29]
	s_mov_b32 m0, s35
	s_nop 0
	global_load_lds_dwordx4 v158, s[28:29]
	s_waitcnt vmcnt(8)
	s_waitcnt lgkmcnt(0)
	s_barrier
	s_setprio 1
	v_mfma_f32_16x16x32_bf16 v[62:65], v[78:81], v[188:191], v[62:65]
	v_mfma_f32_16x16x32_bf16 v[58:61], v[90:93], v[188:191], v[58:61]
	v_mfma_f32_16x16x32_bf16 v[46:49], v[78:81], v[196:199], v[46:49]
	v_mfma_f32_16x16x32_bf16 v[42:45], v[90:93], v[196:199], v[42:45]
	v_mfma_f32_16x16x32_bf16 v[30:33], v[78:81], v[204:207], v[30:33]
	v_mfma_f32_16x16x32_bf16 v[26:29], v[90:93], v[204:207], v[26:29]
	v_mfma_f32_16x16x32_bf16 v[14:17], v[78:81], v[212:215], v[14:17]
	v_mfma_f32_16x16x32_bf16 v[10:13], v[90:93], v[212:215], v[10:13]
	v_mfma_f32_16x16x32_bf16 v[62:65], v[86:89], v[192:195], v[62:65]
	v_mfma_f32_16x16x32_bf16 v[58:61], v[94:97], v[192:195], v[58:61]
	v_mfma_f32_16x16x32_bf16 v[46:49], v[86:89], v[200:203], v[46:49]
	v_mfma_f32_16x16x32_bf16 v[42:45], v[94:97], v[200:203], v[42:45]
	v_mfma_f32_16x16x32_bf16 v[30:33], v[86:89], v[208:211], v[30:33]
	v_mfma_f32_16x16x32_bf16 v[26:29], v[94:97], v[208:211], v[26:29]
	v_mfma_f32_16x16x32_bf16 v[14:17], v[86:89], v[216:219], v[14:17]
	v_mfma_f32_16x16x32_bf16 v[10:13], v[94:97], v[216:219], v[10:13]
	v_mfma_f32_16x16x32_bf16 v[54:57], v[146:149], v[188:191], v[54:57]
	v_mfma_f32_16x16x32_bf16 v[50:53], v[176:179], v[188:191], v[50:53]
	v_mfma_f32_16x16x32_bf16 v[38:41], v[146:149], v[196:199], v[38:41]
	v_mfma_f32_16x16x32_bf16 v[34:37], v[176:179], v[196:199], v[34:37]
	v_mfma_f32_16x16x32_bf16 v[22:25], v[146:149], v[204:207], v[22:25]
	v_mfma_f32_16x16x32_bf16 v[18:21], v[176:179], v[204:207], v[18:21]
	v_mfma_f32_16x16x32_bf16 v[6:9], v[146:149], v[212:215], v[6:9]
	v_mfma_f32_16x16x32_bf16 v[2:5], v[176:179], v[212:215], v[2:5]
	v_mfma_f32_16x16x32_bf16 v[54:57], v[150:153], v[192:195], v[54:57]
	v_mfma_f32_16x16x32_bf16 v[50:53], v[180:183], v[192:195], v[50:53]
	v_mfma_f32_16x16x32_bf16 v[38:41], v[150:153], v[200:203], v[38:41]
	v_mfma_f32_16x16x32_bf16 v[34:37], v[180:183], v[200:203], v[34:37]
	v_mfma_f32_16x16x32_bf16 v[22:25], v[150:153], v[208:211], v[22:25]
	v_mfma_f32_16x16x32_bf16 v[18:21], v[180:183], v[208:211], v[18:21]
	v_mfma_f32_16x16x32_bf16 v[6:9], v[150:153], v[216:219], v[6:9]
	v_mfma_f32_16x16x32_bf16 v[2:5], v[180:183], v[216:219], v[2:5]
	s_setprio 0
	s_barrier
	s_add_i32 s54, 0, 0x18000
	v_add_u32_e32 v1, s54, v173
	s_add_i32 s55, 0, 0x1c000
	ds_read_b128 v[78:81], v1
	ds_read_b128 v[86:89], v1 offset:1024
	ds_read_b128 v[90:93], v1 offset:2048
	ds_read_b128 v[94:97], v1 offset:3072
	v_add_u32_e32 v1, s55, v173
	ds_read_b128 v[146:149], v1
	ds_read_b128 v[150:153], v1 offset:1024
	ds_read_b128 v[176:179], v1 offset:2048
	ds_read_b128 v[180:183], v1 offset:3072
	s_add_u32 s28, s28, 0xb0000
	s_addc_u32 s29, s29, 0
	s_mov_b32 m0, s36
	ds_read_b128 v[188:191], v186 offset:32768
	ds_read_b128 v[192:195], v186 offset:33792
	ds_read_b128 v[196:199], v186 offset:34816
	ds_read_b128 v[200:203], v186 offset:35840
	ds_read_b128 v[204:207], v186 offset:36864
	ds_read_b128 v[208:211], v186 offset:37888
	ds_read_b128 v[212:215], v186 offset:38912
	ds_read_b128 v[216:219], v186 offset:39936
	global_load_lds_dwordx4 v154, s[28:29]
	s_mov_b32 m0, s37
	s_nop 0
	global_load_lds_dwordx4 v158, s[28:29]
	s_waitcnt vmcnt(8)
	s_waitcnt lgkmcnt(0)
	s_barrier
	s_setprio 1
	v_mfma_f32_16x16x32_bf16 v[142:145], v[78:81], v[188:191], v[142:145]
	v_mfma_f32_16x16x32_bf16 v[138:141], v[90:93], v[188:191], v[138:141]
	v_mfma_f32_16x16x32_bf16 v[126:129], v[78:81], v[196:199], v[126:129]
	v_mfma_f32_16x16x32_bf16 v[122:125], v[90:93], v[196:199], v[122:125]
	v_mfma_f32_16x16x32_bf16 v[110:113], v[78:81], v[204:207], v[110:113]
	v_mfma_f32_16x16x32_bf16 v[106:109], v[90:93], v[204:207], v[106:109]
	v_mfma_f32_16x16x32_bf16 v[82:85], v[78:81], v[212:215], v[82:85]
	v_mfma_f32_16x16x32_bf16 v[74:77], v[90:93], v[212:215], v[74:77]
	v_mfma_f32_16x16x32_bf16 v[142:145], v[86:89], v[192:195], v[142:145]
	v_mfma_f32_16x16x32_bf16 v[138:141], v[94:97], v[192:195], v[138:141]
	v_mfma_f32_16x16x32_bf16 v[126:129], v[86:89], v[200:203], v[126:129]
	v_mfma_f32_16x16x32_bf16 v[122:125], v[94:97], v[200:203], v[122:125]
	v_mfma_f32_16x16x32_bf16 v[110:113], v[86:89], v[208:211], v[110:113]
	v_mfma_f32_16x16x32_bf16 v[106:109], v[94:97], v[208:211], v[106:109]
	v_mfma_f32_16x16x32_bf16 v[82:85], v[86:89], v[216:219], v[82:85]
	v_mfma_f32_16x16x32_bf16 v[74:77], v[94:97], v[216:219], v[74:77]
	v_mfma_f32_16x16x32_bf16 v[134:137], v[146:149], v[188:191], v[134:137]
	v_mfma_f32_16x16x32_bf16 v[130:133], v[176:179], v[188:191], v[130:133]
	v_mfma_f32_16x16x32_bf16 v[118:121], v[146:149], v[196:199], v[118:121]
	v_mfma_f32_16x16x32_bf16 v[114:117], v[176:179], v[196:199], v[114:117]
	v_mfma_f32_16x16x32_bf16 v[102:105], v[146:149], v[204:207], v[102:105]
	v_mfma_f32_16x16x32_bf16 v[98:101], v[176:179], v[204:207], v[98:101]
	v_mfma_f32_16x16x32_bf16 v[70:73], v[146:149], v[212:215], v[70:73]
	v_mfma_f32_16x16x32_bf16 v[66:69], v[176:179], v[212:215], v[66:69]
	v_mfma_f32_16x16x32_bf16 v[134:137], v[150:153], v[192:195], v[134:137]
	v_mfma_f32_16x16x32_bf16 v[130:133], v[180:183], v[192:195], v[130:133]
	v_mfma_f32_16x16x32_bf16 v[118:121], v[150:153], v[200:203], v[118:121]
	v_mfma_f32_16x16x32_bf16 v[114:117], v[180:183], v[200:203], v[114:117]
	v_mfma_f32_16x16x32_bf16 v[102:105], v[150:153], v[208:211], v[102:105]
	v_mfma_f32_16x16x32_bf16 v[98:101], v[180:183], v[208:211], v[98:101]
	v_mfma_f32_16x16x32_bf16 v[70:73], v[150:153], v[216:219], v[70:73]
	v_mfma_f32_16x16x32_bf16 v[66:69], v[180:183], v[216:219], v[66:69]
	s_setprio 0
	s_barrier
	s_add_i32 s28, s54, s31
	s_mov_b32 m0, s28
	ds_read_b128 v[188:191], v186 offset:49152
	ds_read_b128 v[192:195], v186 offset:50176
	ds_read_b128 v[196:199], v186 offset:51200
	ds_read_b128 v[200:203], v186 offset:52224
	ds_read_b128 v[204:207], v186 offset:53248
	ds_read_b128 v[208:211], v186 offset:54272
	ds_read_b128 v[212:215], v186 offset:55296
	ds_read_b128 v[216:219], v186 offset:56320
	global_load_lds_dwordx4 v156, s[98:99]
	s_add_i32 m0, s28, 0x2000
	s_add_u32 s26, s26, 0xb0080
	s_addc_u32 s27, s27, 0
	s_add_i32 s28, s55, s31
	global_load_lds_dwordx4 v160, s[98:99]
	s_mov_b32 m0, s28
	s_nop 0
	global_load_lds_dwordx4 v156, s[26:27]
	s_add_i32 m0, s28, 0x2000
	s_nop 0
	global_load_lds_dwordx4 v160, s[26:27]
	s_mov_b32 m0, s41
	s_nop 0
	global_load_lds_dwordx4 v154, s[100:101]
	s_mov_b32 m0, s42
	s_nop 0
	global_load_lds_dwordx4 v158, s[100:101]
	s_waitcnt vmcnt(8)
	s_waitcnt lgkmcnt(0)
	s_barrier
	s_setprio 1
	v_mfma_f32_16x16x32_bf16 v[62:65], v[78:81], v[188:191], v[62:65]
	v_mfma_f32_16x16x32_bf16 v[58:61], v[90:93], v[188:191], v[58:61]
	v_mfma_f32_16x16x32_bf16 v[46:49], v[78:81], v[196:199], v[46:49]
	v_mfma_f32_16x16x32_bf16 v[42:45], v[90:93], v[196:199], v[42:45]
	v_mfma_f32_16x16x32_bf16 v[30:33], v[78:81], v[204:207], v[30:33]
	v_mfma_f32_16x16x32_bf16 v[26:29], v[90:93], v[204:207], v[26:29]
	v_mfma_f32_16x16x32_bf16 v[14:17], v[78:81], v[212:215], v[14:17]
	v_mfma_f32_16x16x32_bf16 v[10:13], v[90:93], v[212:215], v[10:13]
	v_mfma_f32_16x16x32_bf16 v[62:65], v[86:89], v[192:195], v[62:65]
	v_mfma_f32_16x16x32_bf16 v[58:61], v[94:97], v[192:195], v[58:61]
	v_mfma_f32_16x16x32_bf16 v[46:49], v[86:89], v[200:203], v[46:49]
	v_mfma_f32_16x16x32_bf16 v[42:45], v[94:97], v[200:203], v[42:45]
	v_mfma_f32_16x16x32_bf16 v[30:33], v[86:89], v[208:211], v[30:33]
	v_mfma_f32_16x16x32_bf16 v[26:29], v[94:97], v[208:211], v[26:29]
	v_mfma_f32_16x16x32_bf16 v[14:17], v[86:89], v[216:219], v[14:17]
	v_mfma_f32_16x16x32_bf16 v[10:13], v[94:97], v[216:219], v[10:13]
	v_mfma_f32_16x16x32_bf16 v[54:57], v[146:149], v[188:191], v[54:57]
	v_mfma_f32_16x16x32_bf16 v[50:53], v[176:179], v[188:191], v[50:53]
	v_mfma_f32_16x16x32_bf16 v[38:41], v[146:149], v[196:199], v[38:41]
	v_mfma_f32_16x16x32_bf16 v[34:37], v[176:179], v[196:199], v[34:37]
	v_mfma_f32_16x16x32_bf16 v[22:25], v[146:149], v[204:207], v[22:25]
	v_mfma_f32_16x16x32_bf16 v[18:21], v[176:179], v[204:207], v[18:21]
	v_mfma_f32_16x16x32_bf16 v[6:9], v[146:149], v[212:215], v[6:9]
	v_mfma_f32_16x16x32_bf16 v[2:5], v[176:179], v[212:215], v[2:5]
	v_mfma_f32_16x16x32_bf16 v[54:57], v[150:153], v[192:195], v[54:57]
	v_mfma_f32_16x16x32_bf16 v[50:53], v[180:183], v[192:195], v[50:53]
	v_mfma_f32_16x16x32_bf16 v[38:41], v[150:153], v[200:203], v[38:41]
	v_mfma_f32_16x16x32_bf16 v[34:37], v[180:183], v[200:203], v[34:37]
	v_mfma_f32_16x16x32_bf16 v[22:25], v[150:153], v[208:211], v[22:25]
	v_mfma_f32_16x16x32_bf16 v[18:21], v[180:183], v[208:211], v[18:21]
	v_mfma_f32_16x16x32_bf16 v[6:9], v[150:153], v[216:219], v[6:9]
	v_mfma_f32_16x16x32_bf16 v[2:5], v[180:183], v[216:219], v[2:5]
	s_setprio 0
	s_barrier
	s_add_i32 s51, s51, 2
	s_add_u32 s24, s24, 0x100
	s_addc_u32 s25, s25, 0
	s_add_u32 s49, s49, 0x100
	s_addc_u32 s50, s50, 0
	s_cmp_gt_u32 s51, 41
	s_cbranch_scc0 .LBB0_733
	s_and_b64 vcc, exec, s[20:21]
	s_cbranch_vccz .LBB0_736
	s_barrier

.LBB0_1317:
	ds_read_b128 v[30:33], v219
	ds_read_b128 v[54:57], v219 offset:1024
	ds_read_b128 v[118:121], v219 offset:2048
	ds_read_b128 v[122:125], v219 offset:3072
	ds_read_b128 v[146:149], v220
	ds_read_b128 v[150:153], v220 offset:1024
	ds_read_b128 v[154:157], v220 offset:2048
	ds_read_b128 v[158:161], v220 offset:3072
	s_add_u32 s52, s8, 0xfffc0080
	s_addc_u32 s53, s9, -1
	s_cmp_eq_u32 s93, 12
	s_cselect_b32 s55, s45, s53
	s_cselect_b32 s54, s51, s52
	s_cselect_b32 s53, s43, s92
	s_cselect_b32 s52, s90, s91
	s_add_i32 m0, s59, 0xc000
	ds_read_b128 v[162:165], v221
	ds_read_b128 v[166:169], v221 offset:1024
	ds_read_b128 v[196:199], v221 offset:2048
	ds_read_b128 v[200:203], v221 offset:3072
	ds_read_b128 v[204:207], v221 offset:4096
	ds_read_b128 v[208:211], v221 offset:5120
	ds_read_b128 v[224:227], v221 offset:6144
	ds_read_b128 v[228:231], v221 offset:7168
	global_load_lds_dwordx4 v188, s[8:9]
	s_add_i32 m0, s59, 0xe000
	s_nop 0
	global_load_lds_dwordx4 v190, s[8:9]
	s_waitcnt vmcnt(8)
	s_waitcnt lgkmcnt(0)
	s_barrier
	s_setprio 1
	v_mfma_f32_16x16x32_bf16 v[62:65], v[30:33], v[162:165], v[62:65]
	v_mfma_f32_16x16x32_bf16 v[42:45], v[118:121], v[162:165], v[42:45]
	v_mfma_f32_16x16x32_bf16 v[50:53], v[30:33], v[196:199], v[50:53]
	v_mfma_f32_16x16x32_bf16 v[38:41], v[118:121], v[196:199], v[38:41]
	v_mfma_f32_16x16x32_bf16 v[46:49], v[30:33], v[204:207], v[46:49]
	v_mfma_f32_16x16x32_bf16 v[34:37], v[118:121], v[204:207], v[34:37]
	v_mfma_f32_16x16x32_bf16 v[142:145], v[30:33], v[224:227], v[142:145]
	v_mfma_f32_16x16x32_bf16 v[82:85], v[118:121], v[224:227], v[82:85]
	v_mfma_f32_16x16x32_bf16 v[62:65], v[54:57], v[166:169], v[62:65]
	v_mfma_f32_16x16x32_bf16 v[42:45], v[122:125], v[166:169], v[42:45]
	v_mfma_f32_16x16x32_bf16 v[50:53], v[54:57], v[200:203], v[50:53]
	v_mfma_f32_16x16x32_bf16 v[38:41], v[122:125], v[200:203], v[38:41]
	v_mfma_f32_16x16x32_bf16 v[46:49], v[54:57], v[208:211], v[46:49]
	v_mfma_f32_16x16x32_bf16 v[34:37], v[122:125], v[208:211], v[34:37]
	v_mfma_f32_16x16x32_bf16 v[142:145], v[54:57], v[228:231], v[142:145]
	v_mfma_f32_16x16x32_bf16 v[82:85], v[122:125], v[228:231], v[82:85]
	v_mfma_f32_16x16x32_bf16 v[134:137], v[146:149], v[162:165], v[134:137]
	v_mfma_f32_16x16x32_bf16 v[74:77], v[154:157], v[162:165], v[74:77]
	v_mfma_f32_16x16x32_bf16 v[130:133], v[146:149], v[196:199], v[130:133]
	v_mfma_f32_16x16x32_bf16 v[70:73], v[154:157], v[196:199], v[70:73]
	v_mfma_f32_16x16x32_bf16 v[78:81], v[146:149], v[204:207], v[78:81]
	v_mfma_f32_16x16x32_bf16 v[66:69], v[154:157], v[204:207], v[66:69]
	v_mfma_f32_16x16x32_bf16 v[138:141], v[146:149], v[224:227], v[138:141]
	v_mfma_f32_16x16x32_bf16 v[98:101], v[154:157], v[224:227], v[98:101]
	v_mfma_f32_16x16x32_bf16 v[134:137], v[150:153], v[166:169], v[134:137]
	v_mfma_f32_16x16x32_bf16 v[74:77], v[158:161], v[166:169], v[74:77]
	v_mfma_f32_16x16x32_bf16 v[130:133], v[150:153], v[200:203], v[130:133]
	v_mfma_f32_16x16x32_bf16 v[70:73], v[158:161], v[200:203], v[70:73]
	v_mfma_f32_16x16x32_bf16 v[78:81], v[150:153], v[208:211], v[78:81]
	v_mfma_f32_16x16x32_bf16 v[66:69], v[158:161], v[208:211], v[66:69]
	v_mfma_f32_16x16x32_bf16 v[138:141], v[150:153], v[228:231], v[138:141]
	v_mfma_f32_16x16x32_bf16 v[98:101], v[158:161], v[228:231], v[98:101]
	s_setprio 0
	s_barrier
	s_add_u32 s98, s52, 0x80
	s_addc_u32 s99, s53, 0
	s_add_u32 s100, s54, 0x80
	s_addc_u32 s101, s55, 0
	s_add_i32 s84, s75, s57
	s_mov_b32 m0, s84
	ds_read_b128 v[162:165], v221 offset:16384
	ds_read_b128 v[166:169], v221 offset:17408
	ds_read_b128 v[196:199], v221 offset:18432
	ds_read_b128 v[200:203], v221 offset:19456
	ds_read_b128 v[204:207], v221 offset:20480
	ds_read_b128 v[208:211], v221 offset:21504
	ds_read_b128 v[224:227], v221 offset:22528
	ds_read_b128 v[228:231], v221 offset:23552
	global_load_lds_dwordx4 v178, s[52:53]
	s_add_i32 m0, s84, 0x2000
	s_add_u32 s84, s52, 0x40000
	s_addc_u32 s85, s53, 0
	s_add_i32 s86, s76, s57
	global_load_lds_dwordx4 v182, s[52:53]
	s_mov_b32 m0, s86
	s_nop 0
	global_load_lds_dwordx4 v178, s[84:85]
	s_add_i32 m0, s86, 0x2000
	s_nop 0
	global_load_lds_dwordx4 v182, s[84:85]
	s_mov_b32 m0, s59
	s_nop 0
	global_load_lds_dwordx4 v176, s[54:55]
	s_mov_b32 m0, s62
	s_nop 0
	global_load_lds_dwordx4 v180, s[54:55]
	s_waitcnt vmcnt(8)
	s_waitcnt lgkmcnt(0)
	s_barrier
	s_setprio 1
	v_mfma_f32_16x16x32_bf16 v[94:97], v[30:33], v[162:165], v[94:97]
	v_mfma_f32_16x16x32_bf16 v[10:13], v[118:121], v[162:165], v[10:13]
	v_mfma_f32_16x16x32_bf16 v[90:93], v[30:33], v[196:199], v[90:93]
	v_mfma_f32_16x16x32_bf16 v[6:9], v[118:121], v[196:199], v[6:9]
	v_mfma_f32_16x16x32_bf16 v[86:89], v[30:33], v[204:207], v[86:89]
	v_mfma_f32_16x16x32_bf16 v[2:5], v[118:121], v[204:207], v[2:5]
	v_mfma_f32_16x16x32_bf16 v[26:29], v[118:121], v[224:227], v[26:29]
	v_mfma_f32_16x16x32_bf16 v[94:97], v[54:57], v[166:169], v[94:97]
	v_mfma_f32_16x16x32_bf16 v[10:13], v[122:125], v[166:169], v[10:13]
	v_mfma_f32_16x16x32_bf16 v[90:93], v[54:57], v[200:203], v[90:93]
	v_mfma_f32_16x16x32_bf16 v[6:9], v[122:125], v[200:203], v[6:9]
	v_mfma_f32_16x16x32_bf16 v[86:89], v[54:57], v[208:211], v[86:89]
	v_mfma_f32_16x16x32_bf16 v[2:5], v[122:125], v[208:211], v[2:5]
	v_mfma_f32_16x16x32_bf16 v[30:33], v[30:33], v[224:227], v[114:117]
	v_mfma_f32_16x16x32_bf16 v[26:29], v[122:125], v[228:231], v[26:29]
	v_mfma_f32_16x16x32_bf16 v[30:33], v[54:57], v[228:231], v[30:33]
	v_mfma_f32_16x16x32_bf16 v[22:25], v[154:157], v[162:165], v[22:25]
	v_mfma_f32_16x16x32_bf16 v[106:109], v[146:149], v[196:199], v[106:109]
	v_mfma_f32_16x16x32_bf16 v[18:21], v[154:157], v[196:199], v[18:21]
	v_mfma_f32_16x16x32_bf16 v[102:105], v[146:149], v[204:207], v[102:105]
	v_mfma_f32_16x16x32_bf16 v[14:17], v[154:157], v[204:207], v[14:17]
	v_mfma_f32_16x16x32_bf16 v[58:61], v[154:157], v[224:227], v[58:61]
	v_mfma_f32_16x16x32_bf16 v[54:57], v[146:149], v[162:165], v[110:113]
	v_mfma_f32_16x16x32_bf16 v[22:25], v[158:161], v[166:169], v[22:25]
	v_mfma_f32_16x16x32_bf16 v[106:109], v[150:153], v[200:203], v[106:109]
	v_mfma_f32_16x16x32_bf16 v[18:21], v[158:161], v[200:203], v[18:21]
	v_mfma_f32_16x16x32_bf16 v[102:105], v[150:153], v[208:211], v[102:105]
	v_mfma_f32_16x16x32_bf16 v[14:17], v[158:161], v[208:211], v[14:17]
	v_mfma_f32_16x16x32_bf16 v[110:113], v[146:149], v[224:227], v[126:129]
	v_mfma_f32_16x16x32_bf16 v[58:61], v[158:161], v[228:231], v[58:61]
	v_mfma_f32_16x16x32_bf16 v[54:57], v[150:153], v[166:169], v[54:57]
	v_mfma_f32_16x16x32_bf16 v[118:121], v[150:153], v[228:231], v[110:113]
	s_setprio 0
	s_barrier
	s_add_i32 s84, 0, 0x18000
	s_add_i32 s85, 0, 0x1c000
	v_add_u32_e32 v126, s84, v175
	v_add_u32_e32 v158, s85, v175
	ds_read_b128 v[110:113], v126
	ds_read_b128 v[114:117], v126 offset:1024
	ds_read_b128 v[122:125], v126 offset:2048
	ds_read_b128 v[126:129], v126 offset:3072
	ds_read_b128 v[146:149], v158
	ds_read_b128 v[150:153], v158 offset:1024
	ds_read_b128 v[154:157], v158 offset:2048
	ds_read_b128 v[158:161], v158 offset:3072
	s_add_u32 s54, s54, 0x40000
	s_addc_u32 s55, s55, 0
	s_mov_b32 m0, s63
	ds_read_b128 v[162:165], v221 offset:32768
	ds_read_b128 v[166:169], v221 offset:33792
	ds_read_b128 v[196:199], v221 offset:34816
	ds_read_b128 v[200:203], v221 offset:35840
	ds_read_b128 v[204:207], v221 offset:36864
	ds_read_b128 v[208:211], v221 offset:37888
	ds_read_b128 v[224:227], v221 offset:38912
	ds_read_b128 v[228:231], v221 offset:39936
	global_load_lds_dwordx4 v176, s[54:55]
	s_mov_b32 m0, s64
	s_nop 0
	global_load_lds_dwordx4 v180, s[54:55]
	s_waitcnt vmcnt(8)
	s_waitcnt lgkmcnt(0)
	s_barrier
	s_setprio 1
	v_mfma_f32_16x16x32_bf16 v[62:65], v[110:113], v[162:165], v[62:65]
	v_mfma_f32_16x16x32_bf16 v[42:45], v[122:125], v[162:165], v[42:45]
	v_mfma_f32_16x16x32_bf16 v[50:53], v[110:113], v[196:199], v[50:53]
	v_mfma_f32_16x16x32_bf16 v[38:41], v[122:125], v[196:199], v[38:41]
	v_mfma_f32_16x16x32_bf16 v[46:49], v[110:113], v[204:207], v[46:49]
	v_mfma_f32_16x16x32_bf16 v[34:37], v[122:125], v[204:207], v[34:37]
	v_mfma_f32_16x16x32_bf16 v[142:145], v[110:113], v[224:227], v[142:145]
	v_mfma_f32_16x16x32_bf16 v[82:85], v[122:125], v[224:227], v[82:85]
	v_mfma_f32_16x16x32_bf16 v[62:65], v[114:117], v[166:169], v[62:65]
	v_mfma_f32_16x16x32_bf16 v[42:45], v[126:129], v[166:169], v[42:45]
	v_mfma_f32_16x16x32_bf16 v[50:53], v[114:117], v[200:203], v[50:53]
	v_mfma_f32_16x16x32_bf16 v[38:41], v[126:129], v[200:203], v[38:41]
	v_mfma_f32_16x16x32_bf16 v[46:49], v[114:117], v[208:211], v[46:49]
	v_mfma_f32_16x16x32_bf16 v[34:37], v[126:129], v[208:211], v[34:37]
	v_mfma_f32_16x16x32_bf16 v[142:145], v[114:117], v[228:231], v[142:145]
	v_mfma_f32_16x16x32_bf16 v[82:85], v[126:129], v[228:231], v[82:85]
	v_mfma_f32_16x16x32_bf16 v[134:137], v[146:149], v[162:165], v[134:137]
	v_mfma_f32_16x16x32_bf16 v[74:77], v[154:157], v[162:165], v[74:77]
	v_mfma_f32_16x16x32_bf16 v[130:133], v[146:149], v[196:199], v[130:133]
	v_mfma_f32_16x16x32_bf16 v[70:73], v[154:157], v[196:199], v[70:73]
	v_mfma_f32_16x16x32_bf16 v[78:81], v[146:149], v[204:207], v[78:81]
	v_mfma_f32_16x16x32_bf16 v[66:69], v[154:157], v[204:207], v[66:69]
	v_mfma_f32_16x16x32_bf16 v[138:141], v[146:149], v[224:227], v[138:141]
	v_mfma_f32_16x16x32_bf16 v[98:101], v[154:157], v[224:227], v[98:101]
	v_mfma_f32_16x16x32_bf16 v[134:137], v[150:153], v[166:169], v[134:137]
	v_mfma_f32_16x16x32_bf16 v[74:77], v[158:161], v[166:169], v[74:77]
	v_mfma_f32_16x16x32_bf16 v[130:133], v[150:153], v[200:203], v[130:133]
	v_mfma_f32_16x16x32_bf16 v[70:73], v[158:161], v[200:203], v[70:73]
	v_mfma_f32_16x16x32_bf16 v[78:81], v[150:153], v[208:211], v[78:81]
	v_mfma_f32_16x16x32_bf16 v[66:69], v[158:161], v[208:211], v[66:69]
	v_mfma_f32_16x16x32_bf16 v[138:141], v[150:153], v[228:231], v[138:141]
	v_mfma_f32_16x16x32_bf16 v[98:101], v[158:161], v[228:231], v[98:101]
	s_setprio 0
	s_barrier
	s_add_i32 s54, s84, s57
	s_mov_b32 m0, s54
	ds_read_b128 v[162:165], v221 offset:49152
	ds_read_b128 v[166:169], v221 offset:50176
	ds_read_b128 v[196:199], v221 offset:51200
	ds_read_b128 v[200:203], v221 offset:52224
	ds_read_b128 v[204:207], v221 offset:53248
	ds_read_b128 v[208:211], v221 offset:54272
	ds_read_b128 v[224:227], v221 offset:55296
	ds_read_b128 v[228:231], v221 offset:56320
	global_load_lds_dwordx4 v178, s[98:99]
	s_add_i32 m0, s54, 0x2000
	s_add_u32 s52, s52, 0x40080
	s_addc_u32 s53, s53, 0
	s_add_i32 s54, s85, s57
	global_load_lds_dwordx4 v182, s[98:99]
	s_mov_b32 m0, s54
	s_nop 0
	global_load_lds_dwordx4 v178, s[52:53]
	s_add_i32 m0, s54, 0x2000
	s_nop 0
	global_load_lds_dwordx4 v182, s[52:53]
	s_mov_b32 m0, s70
	s_nop 0
	global_load_lds_dwordx4 v176, s[100:101]
	s_mov_b32 m0, s71
	s_nop 0
	global_load_lds_dwordx4 v180, s[100:101]
	s_waitcnt vmcnt(8)
	s_waitcnt lgkmcnt(0)
	s_barrier
	s_setprio 1
	v_mfma_f32_16x16x32_bf16 v[94:97], v[110:113], v[162:165], v[94:97]
	v_mfma_f32_16x16x32_bf16 v[10:13], v[122:125], v[162:165], v[10:13]
	v_mfma_f32_16x16x32_bf16 v[90:93], v[110:113], v[196:199], v[90:93]
	v_mfma_f32_16x16x32_bf16 v[6:9], v[122:125], v[196:199], v[6:9]
	v_mfma_f32_16x16x32_bf16 v[86:89], v[110:113], v[204:207], v[86:89]
	v_mfma_f32_16x16x32_bf16 v[2:5], v[122:125], v[204:207], v[2:5]
	v_mfma_f32_16x16x32_bf16 v[30:33], v[110:113], v[224:227], v[30:33]
	v_mfma_f32_16x16x32_bf16 v[26:29], v[122:125], v[224:227], v[26:29]
	v_mfma_f32_16x16x32_bf16 v[94:97], v[114:117], v[166:169], v[94:97]
	v_mfma_f32_16x16x32_bf16 v[10:13], v[126:129], v[166:169], v[10:13]
	v_mfma_f32_16x16x32_bf16 v[90:93], v[114:117], v[200:203], v[90:93]
	v_mfma_f32_16x16x32_bf16 v[6:9], v[126:129], v[200:203], v[6:9]
	v_mfma_f32_16x16x32_bf16 v[86:89], v[114:117], v[208:211], v[86:89]
	v_mfma_f32_16x16x32_bf16 v[2:5], v[126:129], v[208:211], v[2:5]
	v_mfma_f32_16x16x32_bf16 v[114:117], v[114:117], v[228:231], v[30:33]
	v_mfma_f32_16x16x32_bf16 v[26:29], v[126:129], v[228:231], v[26:29]
	v_mfma_f32_16x16x32_bf16 v[30:33], v[146:149], v[162:165], v[54:57]
	v_mfma_f32_16x16x32_bf16 v[110:113], v[150:153], v[166:169], v[30:33]
	v_mfma_f32_16x16x32_bf16 v[30:33], v[146:149], v[196:199], v[106:109]
	v_mfma_f32_16x16x32_bf16 v[106:109], v[150:153], v[200:203], v[30:33]
	v_mfma_f32_16x16x32_bf16 v[30:33], v[146:149], v[204:207], v[102:105]
	v_mfma_f32_16x16x32_bf16 v[102:105], v[150:153], v[208:211], v[30:33]
	v_mfma_f32_16x16x32_bf16 v[30:33], v[146:149], v[224:227], v[118:121]
	v_mfma_f32_16x16x32_bf16 v[22:25], v[154:157], v[162:165], v[22:25]
	v_mfma_f32_16x16x32_bf16 v[18:21], v[154:157], v[196:199], v[18:21]
	v_mfma_f32_16x16x32_bf16 v[14:17], v[154:157], v[204:207], v[14:17]
	v_mfma_f32_16x16x32_bf16 v[126:129], v[150:153], v[228:231], v[30:33]
	v_mfma_f32_16x16x32_bf16 v[30:33], v[154:157], v[224:227], v[58:61]
	v_mfma_f32_16x16x32_bf16 v[22:25], v[158:161], v[166:169], v[22:25]
	v_mfma_f32_16x16x32_bf16 v[18:21], v[158:161], v[200:203], v[18:21]
	v_mfma_f32_16x16x32_bf16 v[14:17], v[158:161], v[208:211], v[14:17]
	v_mfma_f32_16x16x32_bf16 v[58:61], v[158:161], v[228:231], v[30:33]
	s_setprio 0
	s_barrier
	s_add_i32 s93, s93, 2
	s_add_u32 s8, s8, 0x100
	s_addc_u32 s9, s9, 0
	s_add_u32 s91, s91, 0x100
	s_addc_u32 s92, s92, 0
	s_cmp_gt_u32 s93, 13
	s_cbranch_scc0 .LBB0_1317
	s_and_b64 vcc, exec, s[18:19]
	s_cbranch_vccz .LBB0_1320
	s_barrier

.LBB0_1366:
	s_cbranch_execz .LBB0_1420
	s_waitcnt vmcnt(0)
	s_waitcnt vmcnt(0) lgkmcnt(0)
	v_readfirstlane_b32 s3, v170
	s_nop 0
	s_cmp_gt_u32 s3, 63
	s_cbranch_scc1 .Lei_9
	buffer_inv sc1
.Lei_9:
	s_barrier
	s_mov_b64 s[4:5], exec
	v_readlane_b32 s6, v255, 4
	v_readlane_b32 s7, v255, 5
	s_and_b64 s[6:7], s[4:5], s[6:7]
	s_mov_b64 exec, s[6:7]
	s_cbranch_execz .LBB0_1419
	s_add_i32 s3, 0, 0x22020
	v_mov_b32_e32 v0, s3
	s_waitcnt lgkmcnt(0)
	ds_read_b32 v2, v0
	s_add_i32 s3, 0, 0x22024
	v_mov_b32_e32 v0, s3
	ds_read_b32 v0, v0
	s_waitcnt lgkmcnt(1)
	v_cmp_ne_u32_e32 vcc, 0, v2
	s_cbranch_vccnz .LBB0_1383
	v_readlane_b32 s6, v255, 1
	v_readlane_b32 s7, v255, 2
	s_load_dwordx2 s[12:13], s[6:7], 0x4
	s_add_u32 s6, s88, 0x1200
	s_addc_u32 s7, s89, 0
	s_add_u32 s8, s88, 0x1400
	s_addc_u32 s9, s89, 0
	s_waitcnt lgkmcnt(0)
	s_mul_i32 s3, s12, s33
	s_add_u32 s12, s88, 0x1500
	s_mul_i32 s3, s3, s13
	s_addc_u32 s13, s89, 0
	s_add_u32 s14, s88, 0x1600
	s_addc_u32 s15, s89, 0
	s_add_u32 s16, s88, 0x1700
	s_addc_u32 s17, s89, 0
	s_add_u32 s18, s88, 0x1800
	s_addc_u32 s19, s89, 0
	s_add_u32 s20, s88, 0x1900
	s_addc_u32 s21, s89, 0
	s_add_u32 s22, s88, 0x1a00
	s_addc_u32 s23, s89, 0
	s_add_u32 s24, s88, 0x1b00
	s_addc_u32 s25, s89, 0
	s_add_u32 s26, s88, 0x1c00
	s_addc_u32 s27, s89, 0
	s_add_u32 s28, s88, 0x1d00
	s_addc_u32 s29, s89, 0
	s_add_u32 s30, s88, 0x1e00
	s_addc_u32 s31, s89, 0
	s_add_u32 s34, s88, 0x1f00
	s_addc_u32 s35, s89, 0
	s_add_u32 s36, s88, 0x2000
	s_addc_u32 s37, s89, 0
	s_add_u32 s38, s88, 0x2100
	s_addc_u32 s39, s89, 0
	s_add_u32 s40, s88, 0x2200
	s_addc_u32 s41, s89, 0
	s_add_u32 s42, s88, 0x2300
	s_addc_u32 s43, s89, 0
	s_mov_b32 s50, 1
	v_mov_b32_e32 v16, 0
	s_branch .LBB0_1371

.LBB0_1398:
	s_or_b64 exec, exec, s[12:13]
	s_waitcnt vmcnt(0)
	s_waitcnt vmcnt(0)

.LBB0_1416:
	s_or_b64 exec, exec, s[8:9]
	s_mov_b64 s[8:9], exec
	v_mbcnt_lo_u32_b32 v0, s8, 0
	v_mbcnt_hi_u32_b32 v0, s9, v0
	v_cmp_eq_u32_e32 vcc, 0, v0
	s_waitcnt vmcnt(0)
	s_and_saveexec_b64 s[12:13], vcc
	s_cbranch_execz .LBB0_1418
	s_bcnt1_i32_b64 s3, s[8:9]
	v_mov_b32_e32 v0, 0x2000
	v_mov_b32_e32 v1, s3
	global_atomic_add v0, v1, s[6:7] offset:1024

.LBB0_1463:
	ds_read_b128 v[128:131], v169
	ds_read_b128 v[132:135], v169 offset:1024
	ds_read_b128 v[136:139], v169 offset:2048
	ds_read_b128 v[140:143], v169 offset:3072
	ds_read_b128 v[160:163], v170
	ds_read_b128 v[172:175], v170 offset:1024
	ds_read_b128 v[176:179], v170 offset:2048
	ds_read_b128 v[180:183], v170 offset:3072
	s_add_u32 s18, s16, 0xfff50080
	s_addc_u32 s19, s17, -1
	s_cmp_eq_u32 s45, 40
	s_cselect_b32 s21, s5, s19
	s_cselect_b32 s20, s4, s18
	s_cselect_b32 s19, s15, s44
	s_cselect_b32 s18, s14, s43
	s_add_i32 m0, s26, 0xc000
	ds_read_b128 v[184:187], v171
	ds_read_b128 v[188:191], v171 offset:1024
	ds_read_b128 v[192:195], v171 offset:2048
	ds_read_b128 v[196:199], v171 offset:3072
	ds_read_b128 v[200:203], v171 offset:4096
	ds_read_b128 v[204:207], v171 offset:5120
	ds_read_b128 v[208:211], v171 offset:6144
	ds_read_b128 v[212:215], v171 offset:7168
	global_load_lds_dwordx4 v152, s[16:17]
	s_add_i32 m0, s26, 0xe000
	s_nop 0
	global_load_lds_dwordx4 v154, s[16:17]
	s_waitcnt vmcnt(8)
	s_waitcnt lgkmcnt(0)
	s_barrier
	s_setprio 1
	v_mfma_f32_16x16x32_bf16 v[124:127], v[128:131], v[184:187], v[124:127]
	v_mfma_f32_16x16x32_bf16 v[120:123], v[136:139], v[184:187], v[120:123]
	v_mfma_f32_16x16x32_bf16 v[116:119], v[128:131], v[192:195], v[116:119]
	v_mfma_f32_16x16x32_bf16 v[108:111], v[136:139], v[192:195], v[108:111]
	v_mfma_f32_16x16x32_bf16 v[92:95], v[128:131], v[200:203], v[92:95]
	v_mfma_f32_16x16x32_bf16 v[88:91], v[136:139], v[200:203], v[88:91]
	v_mfma_f32_16x16x32_bf16 v[84:87], v[128:131], v[208:211], v[84:87]
	v_mfma_f32_16x16x32_bf16 v[80:83], v[136:139], v[208:211], v[80:83]
	v_mfma_f32_16x16x32_bf16 v[124:127], v[132:135], v[188:191], v[124:127]
	v_mfma_f32_16x16x32_bf16 v[120:123], v[140:143], v[188:191], v[120:123]
	v_mfma_f32_16x16x32_bf16 v[116:119], v[132:135], v[196:199], v[116:119]
	v_mfma_f32_16x16x32_bf16 v[108:111], v[140:143], v[196:199], v[108:111]
	v_mfma_f32_16x16x32_bf16 v[92:95], v[132:135], v[204:207], v[92:95]
	v_mfma_f32_16x16x32_bf16 v[88:91], v[140:143], v[204:207], v[88:91]
	v_mfma_f32_16x16x32_bf16 v[84:87], v[132:135], v[212:215], v[84:87]
	v_mfma_f32_16x16x32_bf16 v[80:83], v[140:143], v[212:215], v[80:83]
	v_mfma_f32_16x16x32_bf16 v[112:115], v[160:163], v[184:187], v[112:115]
	v_mfma_f32_16x16x32_bf16 v[104:107], v[176:179], v[184:187], v[104:107]
	v_mfma_f32_16x16x32_bf16 v[100:103], v[160:163], v[192:195], v[100:103]
	v_mfma_f32_16x16x32_bf16 v[96:99], v[176:179], v[192:195], v[96:99]
	v_mfma_f32_16x16x32_bf16 v[76:79], v[160:163], v[200:203], v[76:79]
	v_mfma_f32_16x16x32_bf16 v[72:75], v[176:179], v[200:203], v[72:75]
	v_mfma_f32_16x16x32_bf16 v[68:71], v[160:163], v[208:211], v[68:71]
	v_mfma_f32_16x16x32_bf16 v[64:67], v[176:179], v[208:211], v[64:67]
	v_mfma_f32_16x16x32_bf16 v[112:115], v[172:175], v[188:191], v[112:115]
	v_mfma_f32_16x16x32_bf16 v[104:107], v[180:183], v[188:191], v[104:107]
	v_mfma_f32_16x16x32_bf16 v[100:103], v[172:175], v[196:199], v[100:103]
	v_mfma_f32_16x16x32_bf16 v[96:99], v[180:183], v[196:199], v[96:99]
	v_mfma_f32_16x16x32_bf16 v[76:79], v[172:175], v[204:207], v[76:79]
	v_mfma_f32_16x16x32_bf16 v[72:75], v[180:183], v[204:207], v[72:75]
	v_mfma_f32_16x16x32_bf16 v[68:71], v[172:175], v[212:215], v[68:71]
	v_mfma_f32_16x16x32_bf16 v[64:67], v[180:183], v[212:215], v[64:67]
	s_setprio 0
	s_barrier
	s_add_u32 s98, s18, 0x80
	s_addc_u32 s99, s19, 0
	s_add_u32 s100, s20, 0x80
	s_addc_u32 s101, s21, 0
	s_add_i32 s46, s37, s25
	s_mov_b32 m0, s46
	ds_read_b128 v[184:187], v171 offset:16384
	ds_read_b128 v[188:191], v171 offset:17408
	ds_read_b128 v[192:195], v171 offset:18432
	ds_read_b128 v[196:199], v171 offset:19456
	ds_read_b128 v[200:203], v171 offset:20480
	ds_read_b128 v[204:207], v171 offset:21504
	ds_read_b128 v[208:211], v171 offset:22528
	ds_read_b128 v[212:215], v171 offset:23552
	global_load_lds_dwordx4 v146, s[18:19]
	s_add_i32 m0, s46, 0x2000
	s_add_u32 s46, s18, 0xb0000
	s_addc_u32 s47, s19, 0
	s_add_i32 s48, s38, s25
	global_load_lds_dwordx4 v150, s[18:19]
	s_mov_b32 m0, s48
	s_nop 0
	global_load_lds_dwordx4 v146, s[46:47]
	s_add_i32 m0, s48, 0x2000
	s_nop 0
	global_load_lds_dwordx4 v150, s[46:47]
	s_mov_b32 m0, s26
	s_nop 0
	global_load_lds_dwordx4 v144, s[20:21]
	s_mov_b32 m0, s27
	s_nop 0
	global_load_lds_dwordx4 v148, s[20:21]
	s_waitcnt vmcnt(8)
	s_waitcnt lgkmcnt(0)
	s_barrier
	s_setprio 1
	v_mfma_f32_16x16x32_bf16 v[60:63], v[128:131], v[184:187], v[60:63]
	v_mfma_f32_16x16x32_bf16 v[56:59], v[136:139], v[184:187], v[56:59]
	v_mfma_f32_16x16x32_bf16 v[52:55], v[128:131], v[192:195], v[52:55]
	v_mfma_f32_16x16x32_bf16 v[48:51], v[136:139], v[192:195], v[48:51]
	v_mfma_f32_16x16x32_bf16 v[28:31], v[128:131], v[200:203], v[28:31]
	v_mfma_f32_16x16x32_bf16 v[24:27], v[136:139], v[200:203], v[24:27]
	v_mfma_f32_16x16x32_bf16 v[20:23], v[128:131], v[208:211], v[20:23]
	v_mfma_f32_16x16x32_bf16 v[16:19], v[136:139], v[208:211], v[16:19]
	v_mfma_f32_16x16x32_bf16 v[60:63], v[132:135], v[188:191], v[60:63]
	v_mfma_f32_16x16x32_bf16 v[56:59], v[140:143], v[188:191], v[56:59]
	v_mfma_f32_16x16x32_bf16 v[52:55], v[132:135], v[196:199], v[52:55]
	v_mfma_f32_16x16x32_bf16 v[48:51], v[140:143], v[196:199], v[48:51]
	v_mfma_f32_16x16x32_bf16 v[28:31], v[132:135], v[204:207], v[28:31]
	v_mfma_f32_16x16x32_bf16 v[24:27], v[140:143], v[204:207], v[24:27]
	v_mfma_f32_16x16x32_bf16 v[20:23], v[132:135], v[212:215], v[20:23]
	v_mfma_f32_16x16x32_bf16 v[16:19], v[140:143], v[212:215], v[16:19]
	v_mfma_f32_16x16x32_bf16 v[44:47], v[160:163], v[184:187], v[44:47]
	v_mfma_f32_16x16x32_bf16 v[40:43], v[176:179], v[184:187], v[40:43]
	v_mfma_f32_16x16x32_bf16 v[36:39], v[160:163], v[192:195], v[36:39]
	v_mfma_f32_16x16x32_bf16 v[32:35], v[176:179], v[192:195], v[32:35]
	v_mfma_f32_16x16x32_bf16 v[12:15], v[160:163], v[200:203], v[12:15]
	v_mfma_f32_16x16x32_bf16 v[8:11], v[176:179], v[200:203], v[8:11]
	v_mfma_f32_16x16x32_bf16 v[4:7], v[160:163], v[208:211], v[4:7]
	v_mfma_f32_16x16x32_bf16 v[0:3], v[176:179], v[208:211], v[0:3]
	v_mfma_f32_16x16x32_bf16 v[44:47], v[172:175], v[188:191], v[44:47]
	v_mfma_f32_16x16x32_bf16 v[40:43], v[180:183], v[188:191], v[40:43]
	v_mfma_f32_16x16x32_bf16 v[36:39], v[172:175], v[196:199], v[36:39]
	v_mfma_f32_16x16x32_bf16 v[32:35], v[180:183], v[196:199], v[32:35]
	v_mfma_f32_16x16x32_bf16 v[12:15], v[172:175], v[204:207], v[12:15]
	v_mfma_f32_16x16x32_bf16 v[8:11], v[180:183], v[204:207], v[8:11]
	v_mfma_f32_16x16x32_bf16 v[4:7], v[172:175], v[212:215], v[4:7]
	v_mfma_f32_16x16x32_bf16 v[0:3], v[180:183], v[212:215], v[0:3]
	s_setprio 0
	s_barrier
	s_add_i32 s46, 0, 0x18000
	s_add_i32 s47, 0, 0x1c000
	v_add_u32_e32 v140, s46, v167
	v_add_u32_e32 v180, s47, v167
	ds_read_b128 v[128:131], v140
	ds_read_b128 v[132:135], v140 offset:1024
	ds_read_b128 v[136:139], v140 offset:2048
	ds_read_b128 v[140:143], v140 offset:3072
	ds_read_b128 v[160:163], v180
	ds_read_b128 v[172:175], v180 offset:1024
	ds_read_b128 v[176:179], v180 offset:2048
	ds_read_b128 v[180:183], v180 offset:3072
	s_add_u32 s20, s20, 0xb0000
	s_addc_u32 s21, s21, 0
	s_mov_b32 m0, s28
	ds_read_b128 v[184:187], v171 offset:32768
	ds_read_b128 v[188:191], v171 offset:33792
	ds_read_b128 v[192:195], v171 offset:34816
	ds_read_b128 v[196:199], v171 offset:35840
	ds_read_b128 v[200:203], v171 offset:36864
	ds_read_b128 v[204:207], v171 offset:37888
	ds_read_b128 v[208:211], v171 offset:38912
	ds_read_b128 v[212:215], v171 offset:39936
	global_load_lds_dwordx4 v144, s[20:21]
	s_mov_b32 m0, s29
	s_nop 0
	global_load_lds_dwordx4 v148, s[20:21]
	s_waitcnt vmcnt(8)
	s_waitcnt lgkmcnt(0)
	s_barrier
	s_setprio 1
	v_mfma_f32_16x16x32_bf16 v[124:127], v[128:131], v[184:187], v[124:127]
	v_mfma_f32_16x16x32_bf16 v[120:123], v[136:139], v[184:187], v[120:123]
	v_mfma_f32_16x16x32_bf16 v[116:119], v[128:131], v[192:195], v[116:119]
	v_mfma_f32_16x16x32_bf16 v[108:111], v[136:139], v[192:195], v[108:111]
	v_mfma_f32_16x16x32_bf16 v[92:95], v[128:131], v[200:203], v[92:95]
	v_mfma_f32_16x16x32_bf16 v[88:91], v[136:139], v[200:203], v[88:91]
	v_mfma_f32_16x16x32_bf16 v[84:87], v[128:131], v[208:211], v[84:87]
	v_mfma_f32_16x16x32_bf16 v[80:83], v[136:139], v[208:211], v[80:83]
	v_mfma_f32_16x16x32_bf16 v[124:127], v[132:135], v[188:191], v[124:127]
	v_mfma_f32_16x16x32_bf16 v[120:123], v[140:143], v[188:191], v[120:123]
	v_mfma_f32_16x16x32_bf16 v[116:119], v[132:135], v[196:199], v[116:119]
	v_mfma_f32_16x16x32_bf16 v[108:111], v[140:143], v[196:199], v[108:111]
	v_mfma_f32_16x16x32_bf16 v[92:95], v[132:135], v[204:207], v[92:95]
	v_mfma_f32_16x16x32_bf16 v[88:91], v[140:143], v[204:207], v[88:91]
	v_mfma_f32_16x16x32_bf16 v[84:87], v[132:135], v[212:215], v[84:87]
	v_mfma_f32_16x16x32_bf16 v[80:83], v[140:143], v[212:215], v[80:83]
	v_mfma_f32_16x16x32_bf16 v[112:115], v[160:163], v[184:187], v[112:115]
	v_mfma_f32_16x16x32_bf16 v[104:107], v[176:179], v[184:187], v[104:107]
	v_mfma_f32_16x16x32_bf16 v[100:103], v[160:163], v[192:195], v[100:103]
	v_mfma_f32_16x16x32_bf16 v[96:99], v[176:179], v[192:195], v[96:99]
	v_mfma_f32_16x16x32_bf16 v[76:79], v[160:163], v[200:203], v[76:79]
	v_mfma_f32_16x16x32_bf16 v[72:75], v[176:179], v[200:203], v[72:75]
	v_mfma_f32_16x16x32_bf16 v[68:71], v[160:163], v[208:211], v[68:71]
	v_mfma_f32_16x16x32_bf16 v[64:67], v[176:179], v[208:211], v[64:67]
	v_mfma_f32_16x16x32_bf16 v[112:115], v[172:175], v[188:191], v[112:115]
	v_mfma_f32_16x16x32_bf16 v[104:107], v[180:183], v[188:191], v[104:107]
	v_mfma_f32_16x16x32_bf16 v[100:103], v[172:175], v[196:199], v[100:103]
	v_mfma_f32_16x16x32_bf16 v[96:99], v[180:183], v[196:199], v[96:99]
	v_mfma_f32_16x16x32_bf16 v[76:79], v[172:175], v[204:207], v[76:79]
	v_mfma_f32_16x16x32_bf16 v[72:75], v[180:183], v[204:207], v[72:75]
	v_mfma_f32_16x16x32_bf16 v[68:71], v[172:175], v[212:215], v[68:71]
	v_mfma_f32_16x16x32_bf16 v[64:67], v[180:183], v[212:215], v[64:67]
	s_setprio 0
	s_barrier
	s_add_i32 s20, s46, s25
	s_mov_b32 m0, s20
	ds_read_b128 v[184:187], v171 offset:49152
	ds_read_b128 v[188:191], v171 offset:50176
	ds_read_b128 v[192:195], v171 offset:51200
	ds_read_b128 v[196:199], v171 offset:52224
	ds_read_b128 v[200:203], v171 offset:53248
	ds_read_b128 v[204:207], v171 offset:54272
	ds_read_b128 v[208:211], v171 offset:55296
	ds_read_b128 v[212:215], v171 offset:56320
	global_load_lds_dwordx4 v146, s[98:99]
	s_add_i32 m0, s20, 0x2000
	s_add_u32 s18, s18, 0xb0080
	s_addc_u32 s19, s19, 0
	s_add_i32 s20, s47, s25
	global_load_lds_dwordx4 v150, s[98:99]
	s_mov_b32 m0, s20
	s_nop 0
	global_load_lds_dwordx4 v146, s[18:19]
	s_add_i32 m0, s20, 0x2000
	s_nop 0
	global_load_lds_dwordx4 v150, s[18:19]
	s_mov_b32 m0, s35
	s_nop 0
	global_load_lds_dwordx4 v144, s[100:101]
	s_mov_b32 m0, s36
	s_nop 0
	global_load_lds_dwordx4 v148, s[100:101]
	s_waitcnt vmcnt(8)
	s_waitcnt lgkmcnt(0)
	s_barrier
	s_setprio 1
	v_mfma_f32_16x16x32_bf16 v[60:63], v[128:131], v[184:187], v[60:63]
	v_mfma_f32_16x16x32_bf16 v[56:59], v[136:139], v[184:187], v[56:59]
	v_mfma_f32_16x16x32_bf16 v[52:55], v[128:131], v[192:195], v[52:55]
	v_mfma_f32_16x16x32_bf16 v[48:51], v[136:139], v[192:195], v[48:51]
	v_mfma_f32_16x16x32_bf16 v[28:31], v[128:131], v[200:203], v[28:31]
	v_mfma_f32_16x16x32_bf16 v[24:27], v[136:139], v[200:203], v[24:27]
	v_mfma_f32_16x16x32_bf16 v[20:23], v[128:131], v[208:211], v[20:23]
	v_mfma_f32_16x16x32_bf16 v[16:19], v[136:139], v[208:211], v[16:19]
	v_mfma_f32_16x16x32_bf16 v[60:63], v[132:135], v[188:191], v[60:63]
	v_mfma_f32_16x16x32_bf16 v[56:59], v[140:143], v[188:191], v[56:59]
	v_mfma_f32_16x16x32_bf16 v[52:55], v[132:135], v[196:199], v[52:55]
	v_mfma_f32_16x16x32_bf16 v[48:51], v[140:143], v[196:199], v[48:51]
	v_mfma_f32_16x16x32_bf16 v[28:31], v[132:135], v[204:207], v[28:31]
	v_mfma_f32_16x16x32_bf16 v[24:27], v[140:143], v[204:207], v[24:27]
	v_mfma_f32_16x16x32_bf16 v[20:23], v[132:135], v[212:215], v[20:23]
	v_mfma_f32_16x16x32_bf16 v[16:19], v[140:143], v[212:215], v[16:19]
	v_mfma_f32_16x16x32_bf16 v[44:47], v[160:163], v[184:187], v[44:47]
	v_mfma_f32_16x16x32_bf16 v[40:43], v[176:179], v[184:187], v[40:43]
	v_mfma_f32_16x16x32_bf16 v[36:39], v[160:163], v[192:195], v[36:39]
	v_mfma_f32_16x16x32_bf16 v[32:35], v[176:179], v[192:195], v[32:35]
	v_mfma_f32_16x16x32_bf16 v[12:15], v[160:163], v[200:203], v[12:15]
	v_mfma_f32_16x16x32_bf16 v[8:11], v[176:179], v[200:203], v[8:11]
	v_mfma_f32_16x16x32_bf16 v[4:7], v[160:163], v[208:211], v[4:7]
	v_mfma_f32_16x16x32_bf16 v[0:3], v[176:179], v[208:211], v[0:3]
	v_mfma_f32_16x16x32_bf16 v[44:47], v[172:175], v[188:191], v[44:47]
	v_mfma_f32_16x16x32_bf16 v[40:43], v[180:183], v[188:191], v[40:43]
	v_mfma_f32_16x16x32_bf16 v[36:39], v[172:175], v[196:199], v[36:39]
	v_mfma_f32_16x16x32_bf16 v[32:35], v[180:183], v[196:199], v[32:35]
	v_mfma_f32_16x16x32_bf16 v[12:15], v[172:175], v[204:207], v[12:15]
	v_mfma_f32_16x16x32_bf16 v[8:11], v[180:183], v[204:207], v[8:11]
	v_mfma_f32_16x16x32_bf16 v[4:7], v[172:175], v[212:215], v[4:7]
	v_mfma_f32_16x16x32_bf16 v[0:3], v[180:183], v[212:215], v[0:3]
	s_setprio 0
	s_barrier
	s_add_i32 s45, s45, 2
	s_add_u32 s16, s16, 0x100
	s_addc_u32 s17, s17, 0
	s_add_u32 s43, s43, 0x100
	s_addc_u32 s44, s44, 0
	s_cmp_gt_u32 s45, 41
	s_cbranch_scc0 .LBB0_1463
	s_and_b64 vcc, exec, s[12:13]
	s_cbranch_vccz .LBB0_1466
	s_barrier

	.amdhsa_kernel _Z10fwd_kernel4Args
		.amdhsa_group_segment_fixed_size 0
		.amdhsa_private_segment_fixed_size 0
		.amdhsa_kernarg_size 424
		.amdhsa_user_sgpr_count 2
		.amdhsa_user_sgpr_dispatch_ptr 0
		.amdhsa_user_sgpr_queue_ptr 0
		.amdhsa_user_sgpr_kernarg_segment_ptr 1
		.amdhsa_user_sgpr_dispatch_id 0
		.amdhsa_user_sgpr_kernarg_preload_length 0
		.amdhsa_user_sgpr_kernarg_preload_offset 0
		.amdhsa_user_sgpr_private_segment_size 0
		.amdhsa_uses_dynamic_stack 0
		.amdhsa_enable_private_segment 0
		.amdhsa_system_sgpr_workgroup_id_x 1
		.amdhsa_system_sgpr_workgroup_id_y 0
		.amdhsa_system_sgpr_workgroup_id_z 0
		.amdhsa_system_sgpr_workgroup_info 0
		.amdhsa_system_vgpr_workitem_id 2
		.amdhsa_next_free_vgpr 256
		.amdhsa_next_free_sgpr 102
		.amdhsa_accum_offset 256
		.amdhsa_reserve_vcc 1
		.amdhsa_float_round_mode_32 0
		.amdhsa_float_round_mode_16_64 0
		.amdhsa_float_denorm_mode_32 3
		.amdhsa_float_denorm_mode_16_64 3
		.amdhsa_dx10_clamp 1
		.amdhsa_ieee_mode 1
		.amdhsa_fp16_overflow 0
		.amdhsa_tg_split 0
		.amdhsa_exception_fp_ieee_invalid_op 0
		.amdhsa_exception_fp_denorm_src 0
		.amdhsa_exception_fp_ieee_div_zero 0
		.amdhsa_exception_fp_ieee_overflow 0
		.amdhsa_exception_fp_ieee_underflow 0
		.amdhsa_exception_fp_ieee_inexact 0
		.amdhsa_exception_int_div_zero 0
	.end_amdhsa_kernel

amdhsa.kernels:
  - .agpr_count:     0
    .args:
      - .offset:         0
        .size:           168
        .value_kind:     by_value
      - .offset:         168
        .size:           4
        .value_kind:     hidden_block_count_x
      - .offset:         172
        .size:           4
        .value_kind:     hidden_block_count_y
      - .offset:         176
        .size:           4
        .value_kind:     hidden_block_count_z
      - .offset:         180
        .size:           2
        .value_kind:     hidden_group_size_x
      - .offset:         182
        .size:           2
        .value_kind:     hidden_group_size_y
      - .offset:         184
        .size:           2
        .value_kind:     hidden_group_size_z
      - .offset:         186
        .size:           2
        .value_kind:     hidden_remainder_x
      - .offset:         188
        .size:           2
        .value_kind:     hidden_remainder_y
      - .offset:         190
        .size:           2
        .value_kind:     hidden_remainder_z
      - .offset:         208
        .size:           8
        .value_kind:     hidden_global_offset_x
      - .offset:         216
        .size:           8
        .value_kind:     hidden_global_offset_y
      - .offset:         224
        .size:           8
        .value_kind:     hidden_global_offset_z
      - .offset:         232
        .size:           2
        .value_kind:     hidden_grid_dims
      - .offset:         256
        .size:           8
        .value_kind:     hidden_multigrid_sync_arg
      - .offset:         288
        .size:           4
        .value_kind:     hidden_dynamic_lds_size
    .group_segment_fixed_size: 0
    .kernarg_segment_align: 8
    .kernarg_segment_size: 424
    .language:       OpenCL C
    .language_version:
      - 2
      - 0
    .max_flat_workgroup_size: 512
    .name:           _Z10fwd_kernel4Args
    .private_segment_fixed_size: 0
    .sgpr_count:     108
    .sgpr_spill_count: 21
    .symbol:         _Z10fwd_kernel4Args.kd
    .uniform_work_group_size: 1
    .uses_dynamic_stack: false
    .vgpr_count:     256
    .vgpr_spill_count: 0
    .wavefront_size: 64
